# dwconv phase: workgroup walks consecutive tiles, keeps the 46-row window of its two channels in VGPRs, loads only 16 new rows per tile (prefetched), no LDS staging
# speedup vs baseline: 1.0174x; 1.0025x over previous
; __global__ void __launch_bounds__(512, 2) fwd_kernel(Args a) {
;     ...
;         const int c2 = 2 * tid;
;         float wv[31][2];
; #pragma unroll
;         for (int j = 0; j < 31; ++j) { wv[j][0] = a.c_dww[j * DM + c2]; wv[j][1] = a.c_dww[j * DM + c2 + 1]; }
;         const float db0 = a.c_dwb[c2], db1 = a.c_dwb[c2 + 1];
;         const int TPB = (LSEQ + 15) / 16, NT_ = BATCH * TPB;
;         for (int tile = (int)blockIdx.x; tile < NT_; tile += G) {
.LBB0_1161:
	s_cmp_lt_i32 s78, 12
	s_cselect_b64 s[8:9], -1, 0
	s_and_b64 s[0:1], s[8:9], s[0:1]
	s_andn2_b64 vcc, exec, s[0:1]
	s_cbranch_vccnz .LBB0_1197
	s_cmpk_gt_i32 s2, 0x801
	s_cbranch_scc1 .LBB0_1197
	v_readlane_b32 s36, v247, 42
	v_readlane_b32 s40, v247, 46
	v_readlane_b32 s41, v247, 47
	v_lshlrev_b32_e32 v48, 3, v163
	v_mov_b32_e32 v49, 0
	v_readlane_b32 s42, v247, 48
	v_readlane_b32 s43, v247, 49
	v_readlane_b32 s44, v247, 50
	v_readlane_b32 s45, v247, 51
	v_readlane_b32 s46, v247, 52
	v_readlane_b32 s47, v247, 53
	s_mov_b64 s[20:21], s[40:41]
	s_waitcnt lgkmcnt(0)
	v_lshl_add_u64 v[0:1], s[20:21], 0, v[48:49]
	v_add_co_u32_e32 v2, vcc, 0x9000, v0
	s_mov_b64 s[22:23], s[42:43]
	s_nop 0
	v_addc_co_u32_e32 v3, vcc, 0, v1, vcc
	v_add_co_u32_e32 v4, vcc, 0xa000, v0
	v_readlane_b32 s37, v247, 43
	s_nop 0
	v_addc_co_u32_e32 v5, vcc, 0, v1, vcc
	v_add_co_u32_e32 v6, vcc, 0xb000, v0
	v_readlane_b32 s38, v247, 44
	s_nop 0
	v_addc_co_u32_e32 v7, vcc, 0, v1, vcc
	v_add_co_u32_e32 v8, vcc, 0xc000, v0
	v_readlane_b32 s39, v247, 45
	s_nop 0
	v_addc_co_u32_e32 v9, vcc, 0, v1, vcc
	global_load_dwordx2 v[50:51], v[2:3], off
	global_load_dwordx2 v[52:53], v[4:5], off
	global_load_dwordx2 v[54:55], v[6:7], off
	global_load_dwordx2 v[56:57], v[8:9], off
	v_add_co_u32_e32 v2, vcc, 0xd000, v0
	s_waitcnt vmcnt(0)
	v_or_b32_e32 v11, 0xc00, v163
	v_addc_co_u32_e32 v3, vcc, 0, v1, vcc
	v_add_co_u32_e32 v4, vcc, 0xe000, v0
	v_add_u32_e32 v12, 0xe00, v163
	s_nop 0
	v_addc_co_u32_e32 v5, vcc, 0, v1, vcc
	v_add_co_u32_e32 v6, vcc, 0xf000, v0
	v_or_b32_e32 v14, 0x1000, v163
	s_nop 0
	v_addc_co_u32_e32 v7, vcc, 0, v1, vcc
	v_add_co_u32_e32 v8, vcc, 0x10000, v0
	v_add_u32_e32 v15, 0x1200, v163
	s_nop 0
	v_addc_co_u32_e32 v9, vcc, 0, v1, vcc
	global_load_dwordx2 v[58:59], v[2:3], off
	global_load_dwordx2 v[60:61], v[4:5], off
	global_load_dwordx2 v[62:63], v[6:7], off
	global_load_dwordx2 v[64:65], v[8:9], off
	v_add_co_u32_e32 v2, vcc, 0x11000, v0
	v_or_b32_e32 v17, 0x1400, v163
	s_nop 0
	v_addc_co_u32_e32 v3, vcc, 0, v1, vcc
	v_add_co_u32_e32 v4, vcc, 0x12000, v0
	v_add_u32_e32 v18, 0x1600, v163
	s_nop 0
	v_addc_co_u32_e32 v5, vcc, 0, v1, vcc
	v_add_co_u32_e32 v6, vcc, 0x13000, v0
	s_mov_b64 s[24:25], s[44:45]
	s_nop 0
	v_addc_co_u32_e32 v7, vcc, 0, v1, vcc
	v_add_co_u32_e32 v8, vcc, 0x14000, v0
	s_mov_b64 s[26:27], s[46:47]
	s_nop 0
	v_addc_co_u32_e32 v9, vcc, 0, v1, vcc
	global_load_dwordx2 v[66:67], v[2:3], off
	global_load_dwordx2 v[68:69], v[4:5], off
	global_load_dwordx2 v[70:71], v[6:7], off
	global_load_dwordx2 v[72:73], v[8:9], off
	v_add_co_u32_e32 v2, vcc, 0x15000, v0
	v_lshlrev_b32_e32 v156, 2, v163
	s_nop 0
	v_addc_co_u32_e32 v3, vcc, 0, v1, vcc
	v_add_co_u32_e32 v4, vcc, 0x16000, v0
	v_lshlrev_b32_e32 v158, 1, v165
	s_nop 0
	v_addc_co_u32_e32 v5, vcc, 0, v1, vcc
	v_add_co_u32_e32 v6, vcc, 0x17000, v0
	v_readlane_b32 s36, v247, 0
	s_nop 0
	v_addc_co_u32_e32 v7, vcc, 0, v1, vcc
	v_add_co_u32_e32 v8, vcc, 0x18000, v0
	v_lshrrev_b32_e32 v13, 7, v12
	s_nop 0
	v_addc_co_u32_e32 v9, vcc, 0, v1, vcc
	global_load_dwordx2 v[74:75], v[2:3], off
	global_load_dwordx2 v[76:77], v[4:5], off
	global_load_dwordx2 v[78:79], v[6:7], off
	global_load_dwordx2 v[80:81], v[8:9], off
	v_add_co_u32_e32 v2, vcc, 0x19000, v0
	v_lshrrev_b32_e32 v16, 7, v15
	s_nop 0
	v_addc_co_u32_e32 v3, vcc, 0, v1, vcc
	v_add_co_u32_e32 v4, vcc, 0x1a000, v0
	s_movk_i32 s0, 0x1700
	s_nop 0
	v_addc_co_u32_e32 v5, vcc, 0, v1, vcc
	v_add_co_u32_e32 v6, vcc, 0x1b000, v0
	v_lshrrev_b32_e32 v19, 7, v18
	s_nop 0
	v_addc_co_u32_e32 v7, vcc, 0, v1, vcc
	v_add_co_u32_e32 v8, vcc, 0x1c000, v0
	v_lshlrev_b32_e32 v22, 4, v11
	s_nop 0
	v_addc_co_u32_e32 v9, vcc, 0, v1, vcc
	global_load_dwordx2 v[82:83], v[2:3], off
	global_load_dwordx2 v[84:85], v[4:5], off
	global_load_dwordx2 v[86:87], v[6:7], off
	global_load_dwordx2 v[88:89], v[8:9], off
	v_add_co_u32_e32 v2, vcc, 0x1d000, v0
	v_lshlrev_b32_e32 v12, 4, v12
	s_nop 0
	v_addc_co_u32_e32 v3, vcc, 0, v1, vcc
	v_add_co_u32_e32 v4, vcc, 0x1e000, v0
	v_lshlrev_b32_e32 v23, 4, v14
	s_nop 0
	v_addc_co_u32_e32 v5, vcc, 0, v1, vcc
	v_add_co_u32_e32 v6, vcc, 0x1000, v0
	v_lshlrev_b32_e32 v15, 4, v15
	s_nop 0
	v_addc_co_u32_e32 v7, vcc, 0, v1, vcc
	v_add_co_u32_e32 v8, vcc, 0x2000, v0
	v_lshlrev_b32_e32 v24, 4, v17
	s_nop 0
	v_addc_co_u32_e32 v9, vcc, 0, v1, vcc
	global_load_dwordx2 v[90:91], v[2:3], off
	global_load_dwordx2 v[92:93], v[4:5], off
	global_load_dwordx2 v[94:95], v[6:7], off
	global_load_dwordx2 v[96:97], v[8:9], off
	v_add_co_u32_e32 v2, vcc, 0x3000, v0
	v_lshlrev_b32_e32 v18, 4, v18
	s_nop 0
	v_addc_co_u32_e32 v3, vcc, 0, v1, vcc
	v_add_co_u32_e32 v4, vcc, 0x4000, v0
	v_lshlrev_b32_e32 v165, 13, v165
	s_nop 0
	v_addc_co_u32_e32 v5, vcc, 0, v1, vcc
	v_add_co_u32_e32 v6, vcc, 0x5000, v0
	v_add_u32_e32 v157, 0, v156
	s_nop 0
	v_addc_co_u32_e32 v7, vcc, 0, v1, vcc
	v_add_co_u32_e32 v8, vcc, 0x6000, v0
	v_add_u32_e32 v159, 0, v166
	s_nop 0
	v_addc_co_u32_e32 v9, vcc, 0, v1, vcc
	global_load_dwordx2 v[98:99], v[2:3], off
	global_load_dwordx2 v[100:101], v[4:5], off
	global_load_dwordx2 v[102:103], v[6:7], off
	global_load_dwordx2 v[104:105], v[8:9], off
	v_add_co_u32_e32 v2, vcc, 0x7000, v0
	v_or_b32_e32 v5, 0x400, v163
	s_nop 0
	v_addc_co_u32_e32 v3, vcc, 0, v1, vcc
	v_add_co_u32_e32 v0, vcc, 0x8000, v0
	v_add_u32_e32 v6, 0x600, v163
	s_nop 0
	v_addc_co_u32_e32 v1, vcc, 0, v1, vcc
	global_load_dwordx2 v[106:107], v48, s[20:21]
	global_load_dwordx2 v[108:109], v[2:3], off
	global_load_dwordx2 v[110:111], v48, s[22:23]
	global_load_dwordx2 v[112:113], v[0:1], off
	v_lshlrev_b32_e32 v0, 4, v163
	v_add_u32_e32 v3, 0x200, v163
	v_or_b32_e32 v8, 0x800, v163
; __global__ void __launch_bounds__(512, 2) fwd_kernel(Args a) {
;     ...
;         const int TPB = (LSEQ + 15) / 16, NT_ = BATCH * TPB;
;         for (int tile = (int)blockIdx.x; tile < NT_; tile += G) {
;             const int b = tile / TPB, t0 = (tile % TPB) * 16; const size_t rb = (size_t)b * LSEQ;
;             {
;                 u32x4 sv[12];
; #pragma unroll
;                 for (int k = 0; k < 12; ++k) { const int gi = tid + 512 * k, rr = gi >> 7, cc = gi & 127; const int t = t0 - 30 + rr;
;                     sv[k] = (u32x4){0u, 0u, 0u, 0u}; if (gi < 46 * 128 && t >= 0 && t < LSEQ) sv[k] = *(const u32x4*)(BIG + (rb + t) * DM + cc * 8); }
	v_add_u32_e32 v9, 0xa00, v163
	v_and_b32_e32 v48, 0x7f0, v0
	v_lshrrev_b32_e32 v4, 7, v3
	v_lshrrev_b32_e32 v7, 7, v6
	v_lshrrev_b32_e32 v10, 7, v9
	v_lshlrev_b32_e32 v3, 4, v3
	v_lshlrev_b32_e32 v20, 4, v5
	v_lshlrev_b32_e32 v6, 4, v6
	v_lshlrev_b32_e32 v21, 4, v8
	v_lshlrev_b32_e32 v9, 4, v9
	v_lshl_add_u64 v[114:115], s[18:19], 0, v[48:49]
	v_add_u32_e32 v1, 0, v48
	v_mov_b32_e32 v167, v49
	v_lshlrev_b32_e32 v48, 3, v164
	v_readlane_b32 s42, v247, 6
	v_readlane_b32 s43, v247, 7
	v_lshrrev_b32_e32 v2, 7, v163
	v_cmp_gt_u32_e64 s[4:5], s0, v17
	s_movk_i32 s0, 0x100
	v_and_b32_e32 v0, 0x3800, v0
	v_and_b32_e32 v3, 0x7800, v3
	v_and_b32_e32 v20, 0x7800, v20
	v_and_b32_e32 v6, 0xf800, v6
	v_and_b32_e32 v21, 0xb800, v21
	v_and_b32_e32 v9, 0xf800, v9
	v_and_b32_e32 v22, 0xf800, v22
	v_and_b32_e32 v12, 0x1f800, v12
	v_and_b32_e32 v23, 0x13800, v23
	v_and_b32_e32 v15, 0x17800, v15
	v_and_b32_e32 v24, 0x17800, v24
	v_and_b32_e32 v18, 0x16800, v18
	v_or_b32_e32 v25, 0x1000, v165
	v_lshrrev_b32_e32 v17, 7, v17
	v_lshrrev_b32_e32 v14, 7, v14
	v_lshrrev_b32_e32 v11, 7, v11
	v_lshrrev_b32_e32 v8, 7, v8
	v_lshrrev_b32_e32 v5, 7, v5
	v_lshl_add_u64 v[116:117], s[24:25], 0, v[166:167]
	v_lshl_add_u64 v[118:119], s[26:27], 0, v[166:167]
	global_load_dwordx4 v[212:215], v[116:117], off
	global_load_dwordx4 v[228:231], v[118:119], off
	global_load_dwordx4 v[216:219], v[116:117], off offset:1024
	global_load_dwordx4 v[232:235], v[118:119], off offset:1024
	global_load_dwordx4 v[220:223], v[116:117], off offset:2048
	global_load_dwordx4 v[236:239], v[118:119], off offset:2048
	global_load_dwordx4 v[224:227], v[116:117], off offset:3072
	global_load_dwordx4 v[240:243], v[118:119], off offset:3072
	v_lshl_add_u64 v[120:121], s[42:43], 0, v[48:49]
	v_cmp_gt_u32_e64 s[6:7], s0, v163
	v_add_u32_e32 v160, 0x10000, v157
	v_add_u32_e32 v161, 0x10800, v157
	v_add_u32_e32 v167, 0x11000, v157
	v_add_u32_e32 v168, 0x11800, v157
	v_add_u32_e32 v169, 0x12000, v157
	v_add_u32_e32 v170, 0x12800, v157
	v_add_u32_e32 v171, 0x13000, v157
	v_add_u32_e32 v172, 0x13800, v157
	v_add_u32_e32 v173, 0x14000, v157
	v_add_u32_e32 v174, 0x14800, v157
	v_add_u32_e32 v175, 0x15000, v157
	v_add_u32_e32 v176, 0x15800, v157
	v_add_u32_e32 v177, 0x16000, v157
	v_add_u32_e32 v178, 0x16800, v157
	s_lshl_b32 s3, s2, 4
	s_lshl_b32 s14, s88, 4
	v_subrev_u32_e32 v179, 30, v19
	v_subrev_u32_e32 v180, 30, v17
	v_subrev_u32_e32 v181, 30, v16
	v_subrev_u32_e32 v183, 30, v14
	v_subrev_u32_e32 v184, 30, v13
	v_subrev_u32_e32 v185, 30, v11
	v_subrev_u32_e32 v186, 30, v10
	v_subrev_u32_e32 v187, 30, v8
	v_subrev_u32_e32 v188, 30, v7
	v_subrev_u32_e32 v189, 30, v5
	v_subrev_u32_e32 v190, 30, v4
	v_subrev_u32_e32 v191, 30, v2
	s_movk_i32 s15, 0x4010
	v_add_u32_e32 v192, v1, v0
	v_add_u32_e32 v193, v1, v3
	v_add_u32_e32 v194, v1, v20
	v_add_u32_e32 v195, v1, v6
	v_add_u32_e32 v196, v1, v21
	v_add_u32_e32 v197, v1, v9
	v_add_u32_e32 v198, v1, v22
	v_add_u32_e32 v199, v1, v12
	v_add_u32_e32 v200, v1, v23
	v_add_u32_e32 v201, v1, v15
	v_add_u32_e32 v202, v1, v24
	v_add_u32_e32 v203, v1, v18
	v_mov_b32_e32 v204, 0x3727c5ac
	s_mov_b32 s16, 0xf800000
	v_mov_b32_e32 v205, 0x260
	v_add_u32_e32 v206, v159, v25
	s_mov_b32 s17, s2
	v_readlane_b32 s48, v247, 54
	v_readlane_b32 s49, v247, 55
	v_readlane_b32 s50, v247, 56
	v_readlane_b32 s51, v247, 57
	v_readlane_b32 s37, v247, 1
	v_readlane_b32 s38, v247, 2
	v_readlane_b32 s39, v247, 3
	v_readlane_b32 s40, v247, 4
	v_readlane_b32 s41, v247, 5
	s_mov_b32 s64, 0
	s_mov_b32 s65, 0
.Ldw_div:
	s_add_i32 s62, s65, s88
	s_cmp_gt_i32 s62, 0x802
	s_cbranch_scc1 .Ldw_div_done
	s_mov_b32 s65, s62
	s_add_i32 s64, s64, 1
	s_branch .Ldw_div
.Ldw_div_done:
	s_mul_i32 s17, s2, s64
	s_lshl_b32 s3, s17, 4
	s_mov_b32 s63, 0
	s_mov_b32 s61, 1
	s_branch .LBB0_1165
.LBB0_1164:
	s_or_b64 exec, exec, s[12:13]
	s_barrier
	s_add_i32 s63, s63, 1
	s_cmp_lt_i32 s63, s64
	s_cbranch_scc0 .Ldw_after
	s_add_i32 s17, s17, 1
	s_add_i32 s3, s3, 16
	s_branch .LBB0_1165
.Ldw_after:
	s_cmp_eq_u32 s63, s64
	s_cbranch_scc0 .LBB0_1197
	s_sub_i32 s62, 0x802, s65
	s_cmp_lt_u32 s2, s62
	s_cbranch_scc0 .LBB0_1197
	s_add_i32 s17, s65, s2
	s_lshl_b32 s3, s17, 4
.LBB0_1165:
	s_mul_hi_i32 s0, s17, 0x7fe007ff
	s_lshr_b32 s1, s0, 31
	s_ashr_i32 s0, s0, 9
	s_add_i32 s0, s0, s1
	s_mul_i32 s12, s0, 0xffffbff0
	s_add_i32 s12, s12, s3
	s_mul_hi_i32 s11, s0, 0x4010
	s_mul_i32 s10, s0, 0x4010
	s_cmp_eq_u32 s12, 0
	s_cselect_b32 s61, 1, s61
	s_cmp_lg_u32 s61, 0
	s_cbranch_scc0 .Ldw_incr
	s_cmp_eq_u32 s12, 0
	s_cbranch_scc1 .Ldw_full_zero
	s_add_i32 s62, s10, s12
	s_add_i32 s62, s62, -30
	s_lshl_b32 s62, s62, 11
	s_add_u32 s58, s18, s62
	s_addc_u32 s59, s19, 0
	global_load_dword v122, v156, s[58:59]
	global_load_dword v123, v156, s[58:59] offset:2048
	s_add_u32 s58, s58, 0x1000
	s_addc_u32 s59, s59, 0
	global_load_dword v124, v156, s[58:59]
	global_load_dword v125, v156, s[58:59] offset:2048
	s_add_u32 s58, s58, 0x1000
	s_addc_u32 s59, s59, 0
	global_load_dword v126, v156, s[58:59]
	global_load_dword v127, v156, s[58:59] offset:2048
	s_add_u32 s58, s58, 0x1000
	s_addc_u32 s59, s59, 0
	global_load_dword v128, v156, s[58:59]
	global_load_dword v129, v156, s[58:59] offset:2048
	s_add_u32 s58, s58, 0x1000
	s_addc_u32 s59, s59, 0
	global_load_dword v130, v156, s[58:59]
	global_load_dword v131, v156, s[58:59] offset:2048
	s_add_u32 s58, s58, 0x1000
	s_addc_u32 s59, s59, 0
	global_load_dword v132, v156, s[58:59]
	global_load_dword v133, v156, s[58:59] offset:2048
	s_add_u32 s58, s58, 0x1000
	s_addc_u32 s59, s59, 0
	global_load_dword v134, v156, s[58:59]
	global_load_dword v135, v156, s[58:59] offset:2048
	s_add_u32 s58, s58, 0x1000
	s_addc_u32 s59, s59, 0
	global_load_dword v136, v156, s[58:59]
	global_load_dword v137, v156, s[58:59] offset:2048
	s_add_u32 s58, s58, 0x1000
	s_addc_u32 s59, s59, 0
	global_load_dword v138, v156, s[58:59]
	global_load_dword v139, v156, s[58:59] offset:2048
	s_add_u32 s58, s58, 0x1000
	s_addc_u32 s59, s59, 0
	global_load_dword v140, v156, s[58:59]
	global_load_dword v141, v156, s[58:59] offset:2048
	s_add_u32 s58, s58, 0x1000
	s_addc_u32 s59, s59, 0
	global_load_dword v142, v156, s[58:59]
	global_load_dword v143, v156, s[58:59] offset:2048
	s_add_u32 s58, s58, 0x1000
	s_addc_u32 s59, s59, 0
	global_load_dword v144, v156, s[58:59]
	global_load_dword v145, v156, s[58:59] offset:2048
	s_add_u32 s58, s58, 0x1000
	s_addc_u32 s59, s59, 0
	global_load_dword v146, v156, s[58:59]
	global_load_dword v147, v156, s[58:59] offset:2048
	s_add_u32 s58, s58, 0x1000
	s_addc_u32 s59, s59, 0
	global_load_dword v148, v156, s[58:59]
	global_load_dword v149, v156, s[58:59] offset:2048
	s_add_u32 s58, s58, 0x1000
	s_addc_u32 s59, s59, 0
	global_load_dword v150, v156, s[58:59]
	global_load_dword v151, v156, s[58:59] offset:2048
	s_add_u32 s58, s58, 0x1000
	s_addc_u32 s59, s59, 0
	s_branch .Ldw_full_new
; #define LAS __attribute__((address_space(3)))
; __global__ void __launch_bounds__(512, 2) fwd_kernel(Args a) {
;     ...
;             {
;                 u32x4 sv[12];
; #pragma unroll
;                 for (int k = 0; k < 12; ++k) { const int gi = tid + 512 * k, rr = gi >> 7, cc = gi & 127; const int t = t0 - 30 + rr;
;                     sv[k] = (u32x4){0u, 0u, 0u, 0u}; if (gi < 46 * 128 && t >= 0 && t < LSEQ) sv[k] = *(const u32x4*)(BIG + (rb + t) * DM + cc * 8); }
; #pragma unroll
;                 for (int k = 0; k < 12; ++k) { const int gi = tid + 512 * k, rr = gi >> 7, cc = gi & 127; if (gi < 46 * 128) *(LAS u32x4*)(lds + rr * 2048 + cc * 16) = sv[k]; }
.Ldw_full_zero:
	v_mov_b32_e32 v122, 0
	v_mov_b32_e32 v123, 0
	v_mov_b32_e32 v124, 0
	v_mov_b32_e32 v125, 0
	v_mov_b32_e32 v126, 0
	v_mov_b32_e32 v127, 0
	v_mov_b32_e32 v128, 0
	v_mov_b32_e32 v129, 0
	v_mov_b32_e32 v130, 0
	v_mov_b32_e32 v131, 0
	v_mov_b32_e32 v132, 0
	v_mov_b32_e32 v133, 0
	v_mov_b32_e32 v134, 0
	v_mov_b32_e32 v135, 0
	v_mov_b32_e32 v136, 0
	v_mov_b32_e32 v137, 0
	v_mov_b32_e32 v138, 0
	v_mov_b32_e32 v139, 0
	v_mov_b32_e32 v140, 0
	v_mov_b32_e32 v141, 0
	v_mov_b32_e32 v142, 0
	v_mov_b32_e32 v143, 0
	v_mov_b32_e32 v144, 0
	v_mov_b32_e32 v145, 0
	v_mov_b32_e32 v146, 0
	v_mov_b32_e32 v147, 0
	v_mov_b32_e32 v148, 0
	v_mov_b32_e32 v149, 0
	v_mov_b32_e32 v150, 0
	v_mov_b32_e32 v151, 0
	s_lshl_b32 s62, s10, 11
	s_add_u32 s58, s18, s62
	s_addc_u32 s59, s19, 0
.Ldw_full_new:
	global_load_dword v152, v156, s[58:59]
	global_load_dword v153, v156, s[58:59] offset:2048
	s_add_u32 s58, s58, 0x1000
	s_addc_u32 s59, s59, 0
	global_load_dword v154, v156, s[58:59]
	global_load_dword v155, v156, s[58:59] offset:2048
	s_add_u32 s58, s58, 0x1000
	s_addc_u32 s59, s59, 0
	global_load_dword v167, v156, s[58:59]
	global_load_dword v168, v156, s[58:59] offset:2048
	s_add_u32 s58, s58, 0x1000
	s_addc_u32 s59, s59, 0
	global_load_dword v169, v156, s[58:59]
	global_load_dword v170, v156, s[58:59] offset:2048
	s_add_u32 s58, s58, 0x1000
	s_addc_u32 s59, s59, 0
	global_load_dword v171, v156, s[58:59]
	global_load_dword v172, v156, s[58:59] offset:2048
	s_add_u32 s58, s58, 0x1000
	s_addc_u32 s59, s59, 0
	global_load_dword v173, v156, s[58:59]
	global_load_dword v174, v156, s[58:59] offset:2048
	s_add_u32 s58, s58, 0x1000
	s_addc_u32 s59, s59, 0
	global_load_dword v175, v156, s[58:59]
	global_load_dword v176, v156, s[58:59] offset:2048
	s_add_u32 s58, s58, 0x1000
	s_addc_u32 s59, s59, 0
	global_load_dword v177, v156, s[58:59]
	global_load_dword v178, v156, s[58:59] offset:2048
	s_waitcnt vmcnt(0)
	s_branch .Ldw_pref
.Ldw_incr:
	s_waitcnt vmcnt(0)
	v_mov_b32_e32 v122, v138
	v_mov_b32_e32 v123, v139
	v_mov_b32_e32 v124, v140
	v_mov_b32_e32 v125, v141
	v_mov_b32_e32 v126, v142
	v_mov_b32_e32 v127, v143
	v_mov_b32_e32 v128, v144
	v_mov_b32_e32 v129, v145
	v_mov_b32_e32 v130, v146
	v_mov_b32_e32 v131, v147
	v_mov_b32_e32 v132, v148
	v_mov_b32_e32 v133, v149
	v_mov_b32_e32 v134, v150
	v_mov_b32_e32 v135, v151
	v_mov_b32_e32 v136, v152
	v_mov_b32_e32 v137, v153
	v_mov_b32_e32 v138, v154
	v_mov_b32_e32 v139, v155
	v_mov_b32_e32 v140, v167
	v_mov_b32_e32 v141, v168
	v_mov_b32_e32 v142, v169
	v_mov_b32_e32 v143, v170
	v_mov_b32_e32 v144, v171
	v_mov_b32_e32 v145, v172
	v_mov_b32_e32 v146, v173
	v_mov_b32_e32 v147, v174
	v_mov_b32_e32 v148, v175
	v_mov_b32_e32 v149, v176
	v_mov_b32_e32 v150, v177
	v_mov_b32_e32 v151, v178
	v_mov_b32_e32 v152, v183
	v_mov_b32_e32 v153, v184
	v_mov_b32_e32 v154, v185
	v_mov_b32_e32 v155, v186
	v_mov_b32_e32 v167, v187
	v_mov_b32_e32 v168, v188
	v_mov_b32_e32 v169, v189
	v_mov_b32_e32 v170, v190
	v_mov_b32_e32 v171, v191
	v_mov_b32_e32 v172, v192
	v_mov_b32_e32 v173, v193
	v_mov_b32_e32 v174, v194
	v_mov_b32_e32 v175, v195
	v_mov_b32_e32 v176, v196
	v_mov_b32_e32 v177, v197
	v_mov_b32_e32 v178, v198
.Ldw_pref:
	s_mov_b32 s61, 1
	s_add_i32 s62, s63, 1
	s_cmp_lt_i32 s62, s64
	s_cbranch_scc0 .Ldw_conv
	s_add_i32 s62, s12, 16
	s_cmp_lt_i32 s62, 0x4010
	s_cbranch_scc0 .Ldw_conv
	s_mov_b32 s61, 0
	s_add_i32 s62, s62, s10
	s_lshl_b32 s62, s62, 11
	s_add_u32 s58, s18, s62
	s_addc_u32 s59, s19, 0
	global_load_dword v183, v156, s[58:59]
	global_load_dword v184, v156, s[58:59] offset:2048
	s_add_u32 s58, s58, 0x1000
	s_addc_u32 s59, s59, 0
	global_load_dword v185, v156, s[58:59]
	global_load_dword v186, v156, s[58:59] offset:2048
	s_add_u32 s58, s58, 0x1000
	s_addc_u32 s59, s59, 0
	global_load_dword v187, v156, s[58:59]
	global_load_dword v188, v156, s[58:59] offset:2048
	s_add_u32 s58, s58, 0x1000
	s_addc_u32 s59, s59, 0
	global_load_dword v189, v156, s[58:59]
	global_load_dword v190, v156, s[58:59] offset:2048
	s_add_u32 s58, s58, 0x1000
	s_addc_u32 s59, s59, 0
	global_load_dword v191, v156, s[58:59]
	global_load_dword v192, v156, s[58:59] offset:2048
	s_add_u32 s58, s58, 0x1000
	s_addc_u32 s59, s59, 0
	global_load_dword v193, v156, s[58:59]
	global_load_dword v194, v156, s[58:59] offset:2048
	s_add_u32 s58, s58, 0x1000
	s_addc_u32 s59, s59, 0
	global_load_dword v195, v156, s[58:59]
	global_load_dword v196, v156, s[58:59] offset:2048
	s_add_u32 s58, s58, 0x1000
	s_addc_u32 s59, s59, 0
	global_load_dword v197, v156, s[58:59]
	global_load_dword v198, v156, s[58:59] offset:2048
; #define LAS __attribute__((address_space(3)))
; __global__ void __launch_bounds__(512, 2) fwd_kernel(Args a) {
;     ...
;             float acc[16][2];
; #pragma unroll
;             for (int r = 0; r < 16; ++r) { acc[r][0] = db0; acc[r][1] = db1; }
; #pragma unroll
;             for (int j = 0; j < 31; ++j) {
; #pragma unroll
;                 for (int r = 0; r < 16; ++r) { const unsigned w = *(const LAS unsigned*)(lds + (r + j) * 2048 + tid * 4);
;                     acc[r][0] += wv[j][0] * bflo(w); acc[r][1] += wv[j][1] * bfhi(w); } }
.Ldw_conv:
	v_lshlrev_b32_e32 v38, 16, v122
	v_and_b32_e32 v39, 0xffff0000, v122
	v_lshlrev_b32_e32 v40, 16, v123
	v_and_b32_e32 v41, 0xffff0000, v123
	v_pk_fma_f32 v[0:1], v[106:107], v[38:39], v[110:111]
	v_lshlrev_b32_e32 v42, 16, v124
	v_and_b32_e32 v43, 0xffff0000, v124
	v_pk_fma_f32 v[0:1], v[94:95], v[40:41], v[0:1]
	v_pk_fma_f32 v[2:3], v[106:107], v[40:41], v[110:111]
	v_lshlrev_b32_e32 v44, 16, v125
	v_and_b32_e32 v45, 0xffff0000, v125
	v_pk_fma_f32 v[0:1], v[96:97], v[42:43], v[0:1]
	v_pk_fma_f32 v[2:3], v[94:95], v[42:43], v[2:3]
	v_pk_fma_f32 v[4:5], v[106:107], v[42:43], v[110:111]
	v_lshlrev_b32_e32 v38, 16, v126
	v_and_b32_e32 v39, 0xffff0000, v126
	v_pk_fma_f32 v[0:1], v[98:99], v[44:45], v[0:1]
	v_pk_fma_f32 v[2:3], v[96:97], v[44:45], v[2:3]
	v_pk_fma_f32 v[4:5], v[94:95], v[44:45], v[4:5]
	v_pk_fma_f32 v[6:7], v[106:107], v[44:45], v[110:111]
	v_lshlrev_b32_e32 v40, 16, v127
	v_and_b32_e32 v41, 0xffff0000, v127
	v_pk_fma_f32 v[0:1], v[100:101], v[38:39], v[0:1]
	v_pk_fma_f32 v[2:3], v[98:99], v[38:39], v[2:3]
	v_pk_fma_f32 v[4:5], v[96:97], v[38:39], v[4:5]
	v_pk_fma_f32 v[6:7], v[94:95], v[38:39], v[6:7]
	v_pk_fma_f32 v[8:9], v[106:107], v[38:39], v[110:111]
	v_lshlrev_b32_e32 v42, 16, v128
	v_and_b32_e32 v43, 0xffff0000, v128
	v_pk_fma_f32 v[0:1], v[102:103], v[40:41], v[0:1]
	v_pk_fma_f32 v[2:3], v[100:101], v[40:41], v[2:3]
	v_pk_fma_f32 v[4:5], v[98:99], v[40:41], v[4:5]
	v_pk_fma_f32 v[6:7], v[96:97], v[40:41], v[6:7]
	v_pk_fma_f32 v[8:9], v[94:95], v[40:41], v[8:9]
	v_pk_fma_f32 v[10:11], v[106:107], v[40:41], v[110:111]
	v_lshlrev_b32_e32 v44, 16, v129
	v_and_b32_e32 v45, 0xffff0000, v129
	v_pk_fma_f32 v[0:1], v[104:105], v[42:43], v[0:1]
	v_pk_fma_f32 v[2:3], v[102:103], v[42:43], v[2:3]
	v_pk_fma_f32 v[4:5], v[100:101], v[42:43], v[4:5]
	v_pk_fma_f32 v[6:7], v[98:99], v[42:43], v[6:7]
	v_pk_fma_f32 v[8:9], v[96:97], v[42:43], v[8:9]
	v_pk_fma_f32 v[10:11], v[94:95], v[42:43], v[10:11]
	v_pk_fma_f32 v[12:13], v[106:107], v[42:43], v[110:111]
	v_lshlrev_b32_e32 v38, 16, v130
	v_and_b32_e32 v39, 0xffff0000, v130
	v_pk_fma_f32 v[0:1], v[108:109], v[44:45], v[0:1]
	v_pk_fma_f32 v[2:3], v[104:105], v[44:45], v[2:3]
	v_pk_fma_f32 v[4:5], v[102:103], v[44:45], v[4:5]
	v_pk_fma_f32 v[6:7], v[100:101], v[44:45], v[6:7]
	v_pk_fma_f32 v[8:9], v[98:99], v[44:45], v[8:9]
	v_pk_fma_f32 v[10:11], v[96:97], v[44:45], v[10:11]
	v_pk_fma_f32 v[12:13], v[94:95], v[44:45], v[12:13]
	v_pk_fma_f32 v[14:15], v[106:107], v[44:45], v[110:111]
	v_lshlrev_b32_e32 v40, 16, v131
	v_and_b32_e32 v41, 0xffff0000, v131
	v_pk_fma_f32 v[0:1], v[112:113], v[38:39], v[0:1]
	v_pk_fma_f32 v[2:3], v[108:109], v[38:39], v[2:3]
	v_pk_fma_f32 v[4:5], v[104:105], v[38:39], v[4:5]
	v_pk_fma_f32 v[6:7], v[102:103], v[38:39], v[6:7]
	v_pk_fma_f32 v[8:9], v[100:101], v[38:39], v[8:9]
	v_pk_fma_f32 v[10:11], v[98:99], v[38:39], v[10:11]
	v_pk_fma_f32 v[12:13], v[96:97], v[38:39], v[12:13]
	v_pk_fma_f32 v[14:15], v[94:95], v[38:39], v[14:15]
	v_pk_fma_f32 v[16:17], v[106:107], v[38:39], v[110:111]
	v_lshlrev_b32_e32 v42, 16, v132
	v_and_b32_e32 v43, 0xffff0000, v132
	v_pk_fma_f32 v[0:1], v[50:51], v[40:41], v[0:1]
	v_pk_fma_f32 v[2:3], v[112:113], v[40:41], v[2:3]
	v_pk_fma_f32 v[4:5], v[108:109], v[40:41], v[4:5]
	v_pk_fma_f32 v[6:7], v[104:105], v[40:41], v[6:7]
	v_pk_fma_f32 v[8:9], v[102:103], v[40:41], v[8:9]
	v_pk_fma_f32 v[10:11], v[100:101], v[40:41], v[10:11]
	v_pk_fma_f32 v[12:13], v[98:99], v[40:41], v[12:13]
	v_pk_fma_f32 v[14:15], v[96:97], v[40:41], v[14:15]
	v_pk_fma_f32 v[16:17], v[94:95], v[40:41], v[16:17]
	v_pk_fma_f32 v[18:19], v[106:107], v[40:41], v[110:111]
	v_lshlrev_b32_e32 v44, 16, v133
	v_and_b32_e32 v45, 0xffff0000, v133
	v_pk_fma_f32 v[0:1], v[52:53], v[42:43], v[0:1]
	v_pk_fma_f32 v[2:3], v[50:51], v[42:43], v[2:3]
	v_pk_fma_f32 v[4:5], v[112:113], v[42:43], v[4:5]
	v_pk_fma_f32 v[6:7], v[108:109], v[42:43], v[6:7]
	v_pk_fma_f32 v[8:9], v[104:105], v[42:43], v[8:9]
	v_pk_fma_f32 v[10:11], v[102:103], v[42:43], v[10:11]
	v_pk_fma_f32 v[12:13], v[100:101], v[42:43], v[12:13]
	v_pk_fma_f32 v[14:15], v[98:99], v[42:43], v[14:15]
	v_pk_fma_f32 v[16:17], v[96:97], v[42:43], v[16:17]
	v_pk_fma_f32 v[18:19], v[94:95], v[42:43], v[18:19]
	v_pk_fma_f32 v[20:21], v[106:107], v[42:43], v[110:111]
	v_lshlrev_b32_e32 v38, 16, v134
	v_and_b32_e32 v39, 0xffff0000, v134
	v_pk_fma_f32 v[0:1], v[54:55], v[44:45], v[0:1]
	v_pk_fma_f32 v[2:3], v[52:53], v[44:45], v[2:3]
	v_pk_fma_f32 v[4:5], v[50:51], v[44:45], v[4:5]
	v_pk_fma_f32 v[6:7], v[112:113], v[44:45], v[6:7]
	v_pk_fma_f32 v[8:9], v[108:109], v[44:45], v[8:9]
	v_pk_fma_f32 v[10:11], v[104:105], v[44:45], v[10:11]
	v_pk_fma_f32 v[12:13], v[102:103], v[44:45], v[12:13]
	v_pk_fma_f32 v[14:15], v[100:101], v[44:45], v[14:15]
	v_pk_fma_f32 v[16:17], v[98:99], v[44:45], v[16:17]
	v_pk_fma_f32 v[18:19], v[96:97], v[44:45], v[18:19]
	v_pk_fma_f32 v[20:21], v[94:95], v[44:45], v[20:21]
	v_pk_fma_f32 v[22:23], v[106:107], v[44:45], v[110:111]
	v_lshlrev_b32_e32 v40, 16, v135
	v_and_b32_e32 v41, 0xffff0000, v135
	v_pk_fma_f32 v[0:1], v[56:57], v[38:39], v[0:1]
	v_pk_fma_f32 v[2:3], v[54:55], v[38:39], v[2:3]
	v_pk_fma_f32 v[4:5], v[52:53], v[38:39], v[4:5]
	v_pk_fma_f32 v[6:7], v[50:51], v[38:39], v[6:7]
	v_pk_fma_f32 v[8:9], v[112:113], v[38:39], v[8:9]
	v_pk_fma_f32 v[10:11], v[108:109], v[38:39], v[10:11]
	v_pk_fma_f32 v[12:13], v[104:105], v[38:39], v[12:13]
	v_pk_fma_f32 v[14:15], v[102:103], v[38:39], v[14:15]
	v_pk_fma_f32 v[16:17], v[100:101], v[38:39], v[16:17]
	v_pk_fma_f32 v[18:19], v[98:99], v[38:39], v[18:19]
	v_pk_fma_f32 v[20:21], v[96:97], v[38:39], v[20:21]
; #define LAS __attribute__((address_space(3)))
; __global__ void __launch_bounds__(512, 2) fwd_kernel(Args a) {
;     ...
;             float acc[16][2];
; #pragma unroll
;             for (int r = 0; r < 16; ++r) { acc[r][0] = db0; acc[r][1] = db1; }
; #pragma unroll
;             for (int j = 0; j < 31; ++j) {
; #pragma unroll
;                 for (int r = 0; r < 16; ++r) { const unsigned w = *(const LAS unsigned*)(lds + (r + j) * 2048 + tid * 4);
;                     acc[r][0] += wv[j][0] * bflo(w); acc[r][1] += wv[j][1] * bfhi(w); } }
	v_pk_fma_f32 v[22:23], v[94:95], v[38:39], v[22:23]
	v_pk_fma_f32 v[24:25], v[106:107], v[38:39], v[110:111]
	v_lshlrev_b32_e32 v42, 16, v136
	v_and_b32_e32 v43, 0xffff0000, v136
	v_pk_fma_f32 v[0:1], v[58:59], v[40:41], v[0:1]
	v_pk_fma_f32 v[2:3], v[56:57], v[40:41], v[2:3]
	v_pk_fma_f32 v[4:5], v[54:55], v[40:41], v[4:5]
	v_pk_fma_f32 v[6:7], v[52:53], v[40:41], v[6:7]
	v_pk_fma_f32 v[8:9], v[50:51], v[40:41], v[8:9]
	v_pk_fma_f32 v[10:11], v[112:113], v[40:41], v[10:11]
	v_pk_fma_f32 v[12:13], v[108:109], v[40:41], v[12:13]
	v_pk_fma_f32 v[14:15], v[104:105], v[40:41], v[14:15]
	v_pk_fma_f32 v[16:17], v[102:103], v[40:41], v[16:17]
	v_pk_fma_f32 v[18:19], v[100:101], v[40:41], v[18:19]
	v_pk_fma_f32 v[20:21], v[98:99], v[40:41], v[20:21]
	v_pk_fma_f32 v[22:23], v[96:97], v[40:41], v[22:23]
	v_pk_fma_f32 v[24:25], v[94:95], v[40:41], v[24:25]
	v_pk_fma_f32 v[26:27], v[106:107], v[40:41], v[110:111]
	v_lshlrev_b32_e32 v44, 16, v137
	v_and_b32_e32 v45, 0xffff0000, v137
	v_pk_fma_f32 v[0:1], v[60:61], v[42:43], v[0:1]
	v_pk_fma_f32 v[2:3], v[58:59], v[42:43], v[2:3]
	v_pk_fma_f32 v[4:5], v[56:57], v[42:43], v[4:5]
	v_pk_fma_f32 v[6:7], v[54:55], v[42:43], v[6:7]
	v_pk_fma_f32 v[8:9], v[52:53], v[42:43], v[8:9]
	v_pk_fma_f32 v[10:11], v[50:51], v[42:43], v[10:11]
	v_pk_fma_f32 v[12:13], v[112:113], v[42:43], v[12:13]
	v_pk_fma_f32 v[14:15], v[108:109], v[42:43], v[14:15]
	v_pk_fma_f32 v[16:17], v[104:105], v[42:43], v[16:17]
	v_pk_fma_f32 v[18:19], v[102:103], v[42:43], v[18:19]
	v_pk_fma_f32 v[20:21], v[100:101], v[42:43], v[20:21]
	v_pk_fma_f32 v[22:23], v[98:99], v[42:43], v[22:23]
	v_pk_fma_f32 v[24:25], v[96:97], v[42:43], v[24:25]
	v_pk_fma_f32 v[26:27], v[94:95], v[42:43], v[26:27]
	v_pk_fma_f32 v[28:29], v[106:107], v[42:43], v[110:111]
	v_lshlrev_b32_e32 v38, 16, v138
	v_and_b32_e32 v39, 0xffff0000, v138
	v_pk_fma_f32 v[0:1], v[62:63], v[44:45], v[0:1]
	v_pk_fma_f32 v[2:3], v[60:61], v[44:45], v[2:3]
	v_pk_fma_f32 v[4:5], v[58:59], v[44:45], v[4:5]
	v_pk_fma_f32 v[6:7], v[56:57], v[44:45], v[6:7]
	v_pk_fma_f32 v[8:9], v[54:55], v[44:45], v[8:9]
	v_pk_fma_f32 v[10:11], v[52:53], v[44:45], v[10:11]
	v_pk_fma_f32 v[12:13], v[50:51], v[44:45], v[12:13]
	v_pk_fma_f32 v[14:15], v[112:113], v[44:45], v[14:15]
	v_pk_fma_f32 v[16:17], v[108:109], v[44:45], v[16:17]
	v_pk_fma_f32 v[18:19], v[104:105], v[44:45], v[18:19]
	v_pk_fma_f32 v[20:21], v[102:103], v[44:45], v[20:21]
	v_pk_fma_f32 v[22:23], v[100:101], v[44:45], v[22:23]
	v_pk_fma_f32 v[24:25], v[98:99], v[44:45], v[24:25]
	v_pk_fma_f32 v[26:27], v[96:97], v[44:45], v[26:27]
	v_pk_fma_f32 v[28:29], v[94:95], v[44:45], v[28:29]
	v_pk_fma_f32 v[30:31], v[106:107], v[44:45], v[110:111]
	v_lshlrev_b32_e32 v40, 16, v139
	v_and_b32_e32 v41, 0xffff0000, v139
	v_pk_fma_f32 v[0:1], v[64:65], v[38:39], v[0:1]
	v_pk_fma_f32 v[2:3], v[62:63], v[38:39], v[2:3]
	v_pk_fma_f32 v[4:5], v[60:61], v[38:39], v[4:5]
	v_pk_fma_f32 v[6:7], v[58:59], v[38:39], v[6:7]
	v_pk_fma_f32 v[8:9], v[56:57], v[38:39], v[8:9]
	v_pk_fma_f32 v[10:11], v[54:55], v[38:39], v[10:11]
	v_pk_fma_f32 v[12:13], v[52:53], v[38:39], v[12:13]
	v_pk_fma_f32 v[14:15], v[50:51], v[38:39], v[14:15]
	v_pk_fma_f32 v[16:17], v[112:113], v[38:39], v[16:17]
	v_pk_fma_f32 v[18:19], v[108:109], v[38:39], v[18:19]
	v_pk_fma_f32 v[20:21], v[104:105], v[38:39], v[20:21]
	v_pk_fma_f32 v[22:23], v[102:103], v[38:39], v[22:23]
	v_pk_fma_f32 v[24:25], v[100:101], v[38:39], v[24:25]
	v_pk_fma_f32 v[26:27], v[98:99], v[38:39], v[26:27]
	v_pk_fma_f32 v[28:29], v[96:97], v[38:39], v[28:29]
	v_pk_fma_f32 v[30:31], v[94:95], v[38:39], v[30:31]
	v_lshlrev_b32_e32 v42, 16, v140
	v_and_b32_e32 v43, 0xffff0000, v140
	v_pk_fma_f32 v[0:1], v[66:67], v[40:41], v[0:1]
	v_pk_fma_f32 v[2:3], v[64:65], v[40:41], v[2:3]
	v_pk_fma_f32 v[4:5], v[62:63], v[40:41], v[4:5]
	v_pk_fma_f32 v[6:7], v[60:61], v[40:41], v[6:7]
	v_pk_fma_f32 v[8:9], v[58:59], v[40:41], v[8:9]
	v_pk_fma_f32 v[10:11], v[56:57], v[40:41], v[10:11]
	v_pk_fma_f32 v[12:13], v[54:55], v[40:41], v[12:13]
	v_pk_fma_f32 v[14:15], v[52:53], v[40:41], v[14:15]
	v_pk_fma_f32 v[16:17], v[50:51], v[40:41], v[16:17]
	v_pk_fma_f32 v[18:19], v[112:113], v[40:41], v[18:19]
	v_pk_fma_f32 v[20:21], v[108:109], v[40:41], v[20:21]
	v_pk_fma_f32 v[22:23], v[104:105], v[40:41], v[22:23]
	v_pk_fma_f32 v[24:25], v[102:103], v[40:41], v[24:25]
	v_pk_fma_f32 v[26:27], v[100:101], v[40:41], v[26:27]
	v_pk_fma_f32 v[28:29], v[98:99], v[40:41], v[28:29]
	v_pk_fma_f32 v[30:31], v[96:97], v[40:41], v[30:31]
	v_lshlrev_b32_e32 v44, 16, v141
	v_and_b32_e32 v45, 0xffff0000, v141
	v_pk_fma_f32 v[0:1], v[68:69], v[42:43], v[0:1]
	v_pk_fma_f32 v[2:3], v[66:67], v[42:43], v[2:3]
	v_pk_fma_f32 v[4:5], v[64:65], v[42:43], v[4:5]
	v_pk_fma_f32 v[6:7], v[62:63], v[42:43], v[6:7]
	v_pk_fma_f32 v[8:9], v[60:61], v[42:43], v[8:9]
	v_pk_fma_f32 v[10:11], v[58:59], v[42:43], v[10:11]
	v_pk_fma_f32 v[12:13], v[56:57], v[42:43], v[12:13]
	v_pk_fma_f32 v[14:15], v[54:55], v[42:43], v[14:15]
	v_pk_fma_f32 v[16:17], v[52:53], v[42:43], v[16:17]
	v_pk_fma_f32 v[18:19], v[50:51], v[42:43], v[18:19]
	v_pk_fma_f32 v[20:21], v[112:113], v[42:43], v[20:21]
	v_pk_fma_f32 v[22:23], v[108:109], v[42:43], v[22:23]
	v_pk_fma_f32 v[24:25], v[104:105], v[42:43], v[24:25]
	v_pk_fma_f32 v[26:27], v[102:103], v[42:43], v[26:27]
	v_pk_fma_f32 v[28:29], v[100:101], v[42:43], v[28:29]
	v_pk_fma_f32 v[30:31], v[98:99], v[42:43], v[30:31]
	v_lshlrev_b32_e32 v38, 16, v142
	v_and_b32_e32 v39, 0xffff0000, v142
	v_pk_fma_f32 v[0:1], v[70:71], v[44:45], v[0:1]
	v_pk_fma_f32 v[2:3], v[68:69], v[44:45], v[2:3]
	v_pk_fma_f32 v[4:5], v[66:67], v[44:45], v[4:5]
; #define LAS __attribute__((address_space(3)))
; __global__ void __launch_bounds__(512, 2) fwd_kernel(Args a) {
;     ...
;             float acc[16][2];
; #pragma unroll
;             for (int r = 0; r < 16; ++r) { acc[r][0] = db0; acc[r][1] = db1; }
; #pragma unroll
;             for (int j = 0; j < 31; ++j) {
; #pragma unroll
;                 for (int r = 0; r < 16; ++r) { const unsigned w = *(const LAS unsigned*)(lds + (r + j) * 2048 + tid * 4);
;                     acc[r][0] += wv[j][0] * bflo(w); acc[r][1] += wv[j][1] * bfhi(w); } }
	v_pk_fma_f32 v[6:7], v[64:65], v[44:45], v[6:7]
	v_pk_fma_f32 v[8:9], v[62:63], v[44:45], v[8:9]
	v_pk_fma_f32 v[10:11], v[60:61], v[44:45], v[10:11]
	v_pk_fma_f32 v[12:13], v[58:59], v[44:45], v[12:13]
	v_pk_fma_f32 v[14:15], v[56:57], v[44:45], v[14:15]
	v_pk_fma_f32 v[16:17], v[54:55], v[44:45], v[16:17]
	v_pk_fma_f32 v[18:19], v[52:53], v[44:45], v[18:19]
	v_pk_fma_f32 v[20:21], v[50:51], v[44:45], v[20:21]
	v_pk_fma_f32 v[22:23], v[112:113], v[44:45], v[22:23]
	v_pk_fma_f32 v[24:25], v[108:109], v[44:45], v[24:25]
	v_pk_fma_f32 v[26:27], v[104:105], v[44:45], v[26:27]
	v_pk_fma_f32 v[28:29], v[102:103], v[44:45], v[28:29]
	v_pk_fma_f32 v[30:31], v[100:101], v[44:45], v[30:31]
	v_lshlrev_b32_e32 v40, 16, v143
	v_and_b32_e32 v41, 0xffff0000, v143
	v_pk_fma_f32 v[0:1], v[72:73], v[38:39], v[0:1]
	v_pk_fma_f32 v[2:3], v[70:71], v[38:39], v[2:3]
	v_pk_fma_f32 v[4:5], v[68:69], v[38:39], v[4:5]
	v_pk_fma_f32 v[6:7], v[66:67], v[38:39], v[6:7]
	v_pk_fma_f32 v[8:9], v[64:65], v[38:39], v[8:9]
	v_pk_fma_f32 v[10:11], v[62:63], v[38:39], v[10:11]
	v_pk_fma_f32 v[12:13], v[60:61], v[38:39], v[12:13]
	v_pk_fma_f32 v[14:15], v[58:59], v[38:39], v[14:15]
	v_pk_fma_f32 v[16:17], v[56:57], v[38:39], v[16:17]
	v_pk_fma_f32 v[18:19], v[54:55], v[38:39], v[18:19]
	v_pk_fma_f32 v[20:21], v[52:53], v[38:39], v[20:21]
	v_pk_fma_f32 v[22:23], v[50:51], v[38:39], v[22:23]
	v_pk_fma_f32 v[24:25], v[112:113], v[38:39], v[24:25]
	v_pk_fma_f32 v[26:27], v[108:109], v[38:39], v[26:27]
	v_pk_fma_f32 v[28:29], v[104:105], v[38:39], v[28:29]
	v_pk_fma_f32 v[30:31], v[102:103], v[38:39], v[30:31]
	v_lshlrev_b32_e32 v42, 16, v144
	v_and_b32_e32 v43, 0xffff0000, v144
	v_pk_fma_f32 v[0:1], v[74:75], v[40:41], v[0:1]
	v_pk_fma_f32 v[2:3], v[72:73], v[40:41], v[2:3]
	v_pk_fma_f32 v[4:5], v[70:71], v[40:41], v[4:5]
	v_pk_fma_f32 v[6:7], v[68:69], v[40:41], v[6:7]
	v_pk_fma_f32 v[8:9], v[66:67], v[40:41], v[8:9]
	v_pk_fma_f32 v[10:11], v[64:65], v[40:41], v[10:11]
	v_pk_fma_f32 v[12:13], v[62:63], v[40:41], v[12:13]
	v_pk_fma_f32 v[14:15], v[60:61], v[40:41], v[14:15]
	v_pk_fma_f32 v[16:17], v[58:59], v[40:41], v[16:17]
	v_pk_fma_f32 v[18:19], v[56:57], v[40:41], v[18:19]
	v_pk_fma_f32 v[20:21], v[54:55], v[40:41], v[20:21]
	v_pk_fma_f32 v[22:23], v[52:53], v[40:41], v[22:23]
	v_pk_fma_f32 v[24:25], v[50:51], v[40:41], v[24:25]
	v_pk_fma_f32 v[26:27], v[112:113], v[40:41], v[26:27]
	v_pk_fma_f32 v[28:29], v[108:109], v[40:41], v[28:29]
	v_pk_fma_f32 v[30:31], v[104:105], v[40:41], v[30:31]
	v_lshlrev_b32_e32 v44, 16, v145
	v_and_b32_e32 v45, 0xffff0000, v145
	v_pk_fma_f32 v[0:1], v[76:77], v[42:43], v[0:1]
	v_pk_fma_f32 v[2:3], v[74:75], v[42:43], v[2:3]
	v_pk_fma_f32 v[4:5], v[72:73], v[42:43], v[4:5]
	v_pk_fma_f32 v[6:7], v[70:71], v[42:43], v[6:7]
	v_pk_fma_f32 v[8:9], v[68:69], v[42:43], v[8:9]
	v_pk_fma_f32 v[10:11], v[66:67], v[42:43], v[10:11]
	v_pk_fma_f32 v[12:13], v[64:65], v[42:43], v[12:13]
	v_pk_fma_f32 v[14:15], v[62:63], v[42:43], v[14:15]
	v_pk_fma_f32 v[16:17], v[60:61], v[42:43], v[16:17]
	v_pk_fma_f32 v[18:19], v[58:59], v[42:43], v[18:19]
	v_pk_fma_f32 v[20:21], v[56:57], v[42:43], v[20:21]
	v_pk_fma_f32 v[22:23], v[54:55], v[42:43], v[22:23]
	v_pk_fma_f32 v[24:25], v[52:53], v[42:43], v[24:25]
	v_pk_fma_f32 v[26:27], v[50:51], v[42:43], v[26:27]
	v_pk_fma_f32 v[28:29], v[112:113], v[42:43], v[28:29]
	v_pk_fma_f32 v[30:31], v[108:109], v[42:43], v[30:31]
	v_lshlrev_b32_e32 v38, 16, v146
	v_and_b32_e32 v39, 0xffff0000, v146
	v_pk_fma_f32 v[0:1], v[78:79], v[44:45], v[0:1]
	v_pk_fma_f32 v[2:3], v[76:77], v[44:45], v[2:3]
	v_pk_fma_f32 v[4:5], v[74:75], v[44:45], v[4:5]
	v_pk_fma_f32 v[6:7], v[72:73], v[44:45], v[6:7]
	v_pk_fma_f32 v[8:9], v[70:71], v[44:45], v[8:9]
	v_pk_fma_f32 v[10:11], v[68:69], v[44:45], v[10:11]
	v_pk_fma_f32 v[12:13], v[66:67], v[44:45], v[12:13]
	v_pk_fma_f32 v[14:15], v[64:65], v[44:45], v[14:15]
	v_pk_fma_f32 v[16:17], v[62:63], v[44:45], v[16:17]
	v_pk_fma_f32 v[18:19], v[60:61], v[44:45], v[18:19]
	v_pk_fma_f32 v[20:21], v[58:59], v[44:45], v[20:21]
	v_pk_fma_f32 v[22:23], v[56:57], v[44:45], v[22:23]
	v_pk_fma_f32 v[24:25], v[54:55], v[44:45], v[24:25]
	v_pk_fma_f32 v[26:27], v[52:53], v[44:45], v[26:27]
	v_pk_fma_f32 v[28:29], v[50:51], v[44:45], v[28:29]
	v_pk_fma_f32 v[30:31], v[112:113], v[44:45], v[30:31]
	v_lshlrev_b32_e32 v40, 16, v147
	v_and_b32_e32 v41, 0xffff0000, v147
	v_pk_fma_f32 v[0:1], v[80:81], v[38:39], v[0:1]
	v_pk_fma_f32 v[2:3], v[78:79], v[38:39], v[2:3]
	v_pk_fma_f32 v[4:5], v[76:77], v[38:39], v[4:5]
	v_pk_fma_f32 v[6:7], v[74:75], v[38:39], v[6:7]
	v_pk_fma_f32 v[8:9], v[72:73], v[38:39], v[8:9]
	v_pk_fma_f32 v[10:11], v[70:71], v[38:39], v[10:11]
	v_pk_fma_f32 v[12:13], v[68:69], v[38:39], v[12:13]
	v_pk_fma_f32 v[14:15], v[66:67], v[38:39], v[14:15]
	v_pk_fma_f32 v[16:17], v[64:65], v[38:39], v[16:17]
	v_pk_fma_f32 v[18:19], v[62:63], v[38:39], v[18:19]
	v_pk_fma_f32 v[20:21], v[60:61], v[38:39], v[20:21]
	v_pk_fma_f32 v[22:23], v[58:59], v[38:39], v[22:23]
	v_pk_fma_f32 v[24:25], v[56:57], v[38:39], v[24:25]
	v_pk_fma_f32 v[26:27], v[54:55], v[38:39], v[26:27]
	v_pk_fma_f32 v[28:29], v[52:53], v[38:39], v[28:29]
	v_pk_fma_f32 v[30:31], v[50:51], v[38:39], v[30:31]
	v_lshlrev_b32_e32 v42, 16, v148
	v_and_b32_e32 v43, 0xffff0000, v148
	v_pk_fma_f32 v[0:1], v[82:83], v[40:41], v[0:1]
	v_pk_fma_f32 v[2:3], v[80:81], v[40:41], v[2:3]
	v_pk_fma_f32 v[4:5], v[78:79], v[40:41], v[4:5]
	v_pk_fma_f32 v[6:7], v[76:77], v[40:41], v[6:7]
	v_pk_fma_f32 v[8:9], v[74:75], v[40:41], v[8:9]
	v_pk_fma_f32 v[10:11], v[72:73], v[40:41], v[10:11]
	v_pk_fma_f32 v[12:13], v[70:71], v[40:41], v[12:13]
; #define LAS __attribute__((address_space(3)))
; __global__ void __launch_bounds__(512, 2) fwd_kernel(Args a) {
;     ...
;             float acc[16][2];
; #pragma unroll
;             for (int r = 0; r < 16; ++r) { acc[r][0] = db0; acc[r][1] = db1; }
; #pragma unroll
;             for (int j = 0; j < 31; ++j) {
; #pragma unroll
;                 for (int r = 0; r < 16; ++r) { const unsigned w = *(const LAS unsigned*)(lds + (r + j) * 2048 + tid * 4);
;                     acc[r][0] += wv[j][0] * bflo(w); acc[r][1] += wv[j][1] * bfhi(w); } }
	v_pk_fma_f32 v[14:15], v[68:69], v[40:41], v[14:15]
	v_pk_fma_f32 v[16:17], v[66:67], v[40:41], v[16:17]
	v_pk_fma_f32 v[18:19], v[64:65], v[40:41], v[18:19]
	v_pk_fma_f32 v[20:21], v[62:63], v[40:41], v[20:21]
	v_pk_fma_f32 v[22:23], v[60:61], v[40:41], v[22:23]
	v_pk_fma_f32 v[24:25], v[58:59], v[40:41], v[24:25]
	v_pk_fma_f32 v[26:27], v[56:57], v[40:41], v[26:27]
	v_pk_fma_f32 v[28:29], v[54:55], v[40:41], v[28:29]
	v_pk_fma_f32 v[30:31], v[52:53], v[40:41], v[30:31]
	v_lshlrev_b32_e32 v44, 16, v149
	v_and_b32_e32 v45, 0xffff0000, v149
	v_pk_fma_f32 v[0:1], v[84:85], v[42:43], v[0:1]
	v_pk_fma_f32 v[2:3], v[82:83], v[42:43], v[2:3]
	v_pk_fma_f32 v[4:5], v[80:81], v[42:43], v[4:5]
	v_pk_fma_f32 v[6:7], v[78:79], v[42:43], v[6:7]
	v_pk_fma_f32 v[8:9], v[76:77], v[42:43], v[8:9]
	v_pk_fma_f32 v[10:11], v[74:75], v[42:43], v[10:11]
	v_pk_fma_f32 v[12:13], v[72:73], v[42:43], v[12:13]
	v_pk_fma_f32 v[14:15], v[70:71], v[42:43], v[14:15]
	v_pk_fma_f32 v[16:17], v[68:69], v[42:43], v[16:17]
	v_pk_fma_f32 v[18:19], v[66:67], v[42:43], v[18:19]
	v_pk_fma_f32 v[20:21], v[64:65], v[42:43], v[20:21]
	v_pk_fma_f32 v[22:23], v[62:63], v[42:43], v[22:23]
	v_pk_fma_f32 v[24:25], v[60:61], v[42:43], v[24:25]
	v_pk_fma_f32 v[26:27], v[58:59], v[42:43], v[26:27]
	v_pk_fma_f32 v[28:29], v[56:57], v[42:43], v[28:29]
	v_pk_fma_f32 v[30:31], v[54:55], v[42:43], v[30:31]
	v_lshlrev_b32_e32 v38, 16, v150
	v_and_b32_e32 v39, 0xffff0000, v150
	v_pk_fma_f32 v[0:1], v[86:87], v[44:45], v[0:1]
	v_pk_fma_f32 v[2:3], v[84:85], v[44:45], v[2:3]
	v_pk_fma_f32 v[4:5], v[82:83], v[44:45], v[4:5]
	v_pk_fma_f32 v[6:7], v[80:81], v[44:45], v[6:7]
	v_pk_fma_f32 v[8:9], v[78:79], v[44:45], v[8:9]
	v_pk_fma_f32 v[10:11], v[76:77], v[44:45], v[10:11]
	v_pk_fma_f32 v[12:13], v[74:75], v[44:45], v[12:13]
	v_pk_fma_f32 v[14:15], v[72:73], v[44:45], v[14:15]
	v_pk_fma_f32 v[16:17], v[70:71], v[44:45], v[16:17]
	v_pk_fma_f32 v[18:19], v[68:69], v[44:45], v[18:19]
	v_pk_fma_f32 v[20:21], v[66:67], v[44:45], v[20:21]
	v_pk_fma_f32 v[22:23], v[64:65], v[44:45], v[22:23]
	v_pk_fma_f32 v[24:25], v[62:63], v[44:45], v[24:25]
	v_pk_fma_f32 v[26:27], v[60:61], v[44:45], v[26:27]
	v_pk_fma_f32 v[28:29], v[58:59], v[44:45], v[28:29]
	v_pk_fma_f32 v[30:31], v[56:57], v[44:45], v[30:31]
	v_lshlrev_b32_e32 v40, 16, v151
	v_and_b32_e32 v41, 0xffff0000, v151
	v_pk_fma_f32 v[0:1], v[88:89], v[38:39], v[0:1]
	v_pk_fma_f32 v[2:3], v[86:87], v[38:39], v[2:3]
	v_pk_fma_f32 v[4:5], v[84:85], v[38:39], v[4:5]
	v_pk_fma_f32 v[6:7], v[82:83], v[38:39], v[6:7]
	v_pk_fma_f32 v[8:9], v[80:81], v[38:39], v[8:9]
	v_pk_fma_f32 v[10:11], v[78:79], v[38:39], v[10:11]
	v_pk_fma_f32 v[12:13], v[76:77], v[38:39], v[12:13]
	v_pk_fma_f32 v[14:15], v[74:75], v[38:39], v[14:15]
	v_pk_fma_f32 v[16:17], v[72:73], v[38:39], v[16:17]
	v_pk_fma_f32 v[18:19], v[70:71], v[38:39], v[18:19]
	v_pk_fma_f32 v[20:21], v[68:69], v[38:39], v[20:21]
	v_pk_fma_f32 v[22:23], v[66:67], v[38:39], v[22:23]
	v_pk_fma_f32 v[24:25], v[64:65], v[38:39], v[24:25]
	v_pk_fma_f32 v[26:27], v[62:63], v[38:39], v[26:27]
	v_pk_fma_f32 v[28:29], v[60:61], v[38:39], v[28:29]
	v_pk_fma_f32 v[30:31], v[58:59], v[38:39], v[30:31]
	v_lshlrev_b32_e32 v42, 16, v152
	v_and_b32_e32 v43, 0xffff0000, v152
	v_pk_fma_f32 v[0:1], v[90:91], v[40:41], v[0:1]
	v_pk_fma_f32 v[2:3], v[88:89], v[40:41], v[2:3]
	v_pk_fma_f32 v[4:5], v[86:87], v[40:41], v[4:5]
	v_pk_fma_f32 v[6:7], v[84:85], v[40:41], v[6:7]
	v_pk_fma_f32 v[8:9], v[82:83], v[40:41], v[8:9]
	v_pk_fma_f32 v[10:11], v[80:81], v[40:41], v[10:11]
	v_pk_fma_f32 v[12:13], v[78:79], v[40:41], v[12:13]
	v_pk_fma_f32 v[14:15], v[76:77], v[40:41], v[14:15]
	v_pk_fma_f32 v[16:17], v[74:75], v[40:41], v[16:17]
	v_pk_fma_f32 v[18:19], v[72:73], v[40:41], v[18:19]
	v_pk_fma_f32 v[20:21], v[70:71], v[40:41], v[20:21]
	v_pk_fma_f32 v[22:23], v[68:69], v[40:41], v[22:23]
	v_pk_fma_f32 v[24:25], v[66:67], v[40:41], v[24:25]
	v_pk_fma_f32 v[26:27], v[64:65], v[40:41], v[26:27]
	v_pk_fma_f32 v[28:29], v[62:63], v[40:41], v[28:29]
	v_pk_fma_f32 v[30:31], v[60:61], v[40:41], v[30:31]
	v_lshlrev_b32_e32 v44, 16, v153
	v_and_b32_e32 v45, 0xffff0000, v153
	v_pk_fma_f32 v[0:1], v[92:93], v[42:43], v[0:1]
	v_pk_fma_f32 v[2:3], v[90:91], v[42:43], v[2:3]
	v_pk_fma_f32 v[4:5], v[88:89], v[42:43], v[4:5]
	v_pk_fma_f32 v[6:7], v[86:87], v[42:43], v[6:7]
	v_pk_fma_f32 v[8:9], v[84:85], v[42:43], v[8:9]
	v_pk_fma_f32 v[10:11], v[82:83], v[42:43], v[10:11]
	v_pk_fma_f32 v[12:13], v[80:81], v[42:43], v[12:13]
	v_pk_fma_f32 v[14:15], v[78:79], v[42:43], v[14:15]
	v_pk_fma_f32 v[16:17], v[76:77], v[42:43], v[16:17]
	v_pk_fma_f32 v[18:19], v[74:75], v[42:43], v[18:19]
	v_pk_fma_f32 v[20:21], v[72:73], v[42:43], v[20:21]
	v_pk_fma_f32 v[22:23], v[70:71], v[42:43], v[22:23]
	v_pk_fma_f32 v[24:25], v[68:69], v[42:43], v[24:25]
	v_pk_fma_f32 v[26:27], v[66:67], v[42:43], v[26:27]
	v_pk_fma_f32 v[28:29], v[64:65], v[42:43], v[28:29]
	v_pk_fma_f32 v[30:31], v[62:63], v[42:43], v[30:31]
	v_lshlrev_b32_e32 v38, 16, v154
	v_and_b32_e32 v39, 0xffff0000, v154
	v_pk_fma_f32 v[2:3], v[92:93], v[44:45], v[2:3]
	v_pk_fma_f32 v[4:5], v[90:91], v[44:45], v[4:5]
	v_pk_fma_f32 v[6:7], v[88:89], v[44:45], v[6:7]
	v_pk_fma_f32 v[8:9], v[86:87], v[44:45], v[8:9]
	v_pk_fma_f32 v[10:11], v[84:85], v[44:45], v[10:11]
	v_pk_fma_f32 v[12:13], v[82:83], v[44:45], v[12:13]
	v_pk_fma_f32 v[14:15], v[80:81], v[44:45], v[14:15]
	v_pk_fma_f32 v[16:17], v[78:79], v[44:45], v[16:17]
	v_pk_fma_f32 v[18:19], v[76:77], v[44:45], v[18:19]
	v_pk_fma_f32 v[20:21], v[74:75], v[44:45], v[20:21]
	v_pk_fma_f32 v[22:23], v[72:73], v[44:45], v[22:23]
	v_pk_fma_f32 v[24:25], v[70:71], v[44:45], v[24:25]
; #define LAS __attribute__((address_space(3)))
; __global__ void __launch_bounds__(512, 2) fwd_kernel(Args a) {
;     ...
;             float acc[16][2];
; #pragma unroll
;             for (int r = 0; r < 16; ++r) { acc[r][0] = db0; acc[r][1] = db1; }
; #pragma unroll
;             for (int j = 0; j < 31; ++j) {
; #pragma unroll
;                 for (int r = 0; r < 16; ++r) { const unsigned w = *(const LAS unsigned*)(lds + (r + j) * 2048 + tid * 4);
;                     acc[r][0] += wv[j][0] * bflo(w); acc[r][1] += wv[j][1] * bfhi(w); } }
	v_pk_fma_f32 v[26:27], v[68:69], v[44:45], v[26:27]
	v_pk_fma_f32 v[28:29], v[66:67], v[44:45], v[28:29]
	v_pk_fma_f32 v[30:31], v[64:65], v[44:45], v[30:31]
	v_lshlrev_b32_e32 v40, 16, v155
	v_and_b32_e32 v41, 0xffff0000, v155
	v_pk_fma_f32 v[4:5], v[92:93], v[38:39], v[4:5]
	v_pk_fma_f32 v[6:7], v[90:91], v[38:39], v[6:7]
	v_pk_fma_f32 v[8:9], v[88:89], v[38:39], v[8:9]
	v_pk_fma_f32 v[10:11], v[86:87], v[38:39], v[10:11]
	v_pk_fma_f32 v[12:13], v[84:85], v[38:39], v[12:13]
	v_pk_fma_f32 v[14:15], v[82:83], v[38:39], v[14:15]
	v_pk_fma_f32 v[16:17], v[80:81], v[38:39], v[16:17]
	v_pk_fma_f32 v[18:19], v[78:79], v[38:39], v[18:19]
	v_pk_fma_f32 v[20:21], v[76:77], v[38:39], v[20:21]
	v_pk_fma_f32 v[22:23], v[74:75], v[38:39], v[22:23]
	v_pk_fma_f32 v[24:25], v[72:73], v[38:39], v[24:25]
	v_pk_fma_f32 v[26:27], v[70:71], v[38:39], v[26:27]
	v_pk_fma_f32 v[28:29], v[68:69], v[38:39], v[28:29]
	v_pk_fma_f32 v[30:31], v[66:67], v[38:39], v[30:31]
	v_lshlrev_b32_e32 v42, 16, v167
	v_and_b32_e32 v43, 0xffff0000, v167
	v_pk_fma_f32 v[6:7], v[92:93], v[40:41], v[6:7]
	v_pk_fma_f32 v[8:9], v[90:91], v[40:41], v[8:9]
	v_pk_fma_f32 v[10:11], v[88:89], v[40:41], v[10:11]
	v_pk_fma_f32 v[12:13], v[86:87], v[40:41], v[12:13]
	v_pk_fma_f32 v[14:15], v[84:85], v[40:41], v[14:15]
	v_pk_fma_f32 v[16:17], v[82:83], v[40:41], v[16:17]
	v_pk_fma_f32 v[18:19], v[80:81], v[40:41], v[18:19]
	v_pk_fma_f32 v[20:21], v[78:79], v[40:41], v[20:21]
	v_pk_fma_f32 v[22:23], v[76:77], v[40:41], v[22:23]
	v_pk_fma_f32 v[24:25], v[74:75], v[40:41], v[24:25]
	v_pk_fma_f32 v[26:27], v[72:73], v[40:41], v[26:27]
	v_pk_fma_f32 v[28:29], v[70:71], v[40:41], v[28:29]
	v_pk_fma_f32 v[30:31], v[68:69], v[40:41], v[30:31]
	v_lshlrev_b32_e32 v44, 16, v168
	v_and_b32_e32 v45, 0xffff0000, v168
	v_pk_fma_f32 v[8:9], v[92:93], v[42:43], v[8:9]
	v_pk_fma_f32 v[10:11], v[90:91], v[42:43], v[10:11]
	v_pk_fma_f32 v[12:13], v[88:89], v[42:43], v[12:13]
	v_pk_fma_f32 v[14:15], v[86:87], v[42:43], v[14:15]
	v_pk_fma_f32 v[16:17], v[84:85], v[42:43], v[16:17]
	v_pk_fma_f32 v[18:19], v[82:83], v[42:43], v[18:19]
	v_pk_fma_f32 v[20:21], v[80:81], v[42:43], v[20:21]
	v_pk_fma_f32 v[22:23], v[78:79], v[42:43], v[22:23]
	v_pk_fma_f32 v[24:25], v[76:77], v[42:43], v[24:25]
	v_pk_fma_f32 v[26:27], v[74:75], v[42:43], v[26:27]
	v_pk_fma_f32 v[28:29], v[72:73], v[42:43], v[28:29]
	v_pk_fma_f32 v[30:31], v[70:71], v[42:43], v[30:31]
	v_lshlrev_b32_e32 v38, 16, v169
	v_and_b32_e32 v39, 0xffff0000, v169
	v_pk_fma_f32 v[10:11], v[92:93], v[44:45], v[10:11]
	v_pk_fma_f32 v[12:13], v[90:91], v[44:45], v[12:13]
	v_pk_fma_f32 v[14:15], v[88:89], v[44:45], v[14:15]
	v_pk_fma_f32 v[16:17], v[86:87], v[44:45], v[16:17]
	v_pk_fma_f32 v[18:19], v[84:85], v[44:45], v[18:19]
	v_pk_fma_f32 v[20:21], v[82:83], v[44:45], v[20:21]
	v_pk_fma_f32 v[22:23], v[80:81], v[44:45], v[22:23]
	v_pk_fma_f32 v[24:25], v[78:79], v[44:45], v[24:25]
	v_pk_fma_f32 v[26:27], v[76:77], v[44:45], v[26:27]
	v_pk_fma_f32 v[28:29], v[74:75], v[44:45], v[28:29]
	v_pk_fma_f32 v[30:31], v[72:73], v[44:45], v[30:31]
	v_lshlrev_b32_e32 v40, 16, v170
	v_and_b32_e32 v41, 0xffff0000, v170
	v_pk_fma_f32 v[12:13], v[92:93], v[38:39], v[12:13]
	v_pk_fma_f32 v[14:15], v[90:91], v[38:39], v[14:15]
	v_pk_fma_f32 v[16:17], v[88:89], v[38:39], v[16:17]
	v_pk_fma_f32 v[18:19], v[86:87], v[38:39], v[18:19]
	v_pk_fma_f32 v[20:21], v[84:85], v[38:39], v[20:21]
	v_pk_fma_f32 v[22:23], v[82:83], v[38:39], v[22:23]
	v_pk_fma_f32 v[24:25], v[80:81], v[38:39], v[24:25]
	v_pk_fma_f32 v[26:27], v[78:79], v[38:39], v[26:27]
	v_pk_fma_f32 v[28:29], v[76:77], v[38:39], v[28:29]
	v_pk_fma_f32 v[30:31], v[74:75], v[38:39], v[30:31]
	v_lshlrev_b32_e32 v42, 16, v171
	v_and_b32_e32 v43, 0xffff0000, v171
	v_pk_fma_f32 v[14:15], v[92:93], v[40:41], v[14:15]
	v_pk_fma_f32 v[16:17], v[90:91], v[40:41], v[16:17]
	v_pk_fma_f32 v[18:19], v[88:89], v[40:41], v[18:19]
	v_pk_fma_f32 v[20:21], v[86:87], v[40:41], v[20:21]
	v_pk_fma_f32 v[22:23], v[84:85], v[40:41], v[22:23]
	v_pk_fma_f32 v[24:25], v[82:83], v[40:41], v[24:25]
	v_pk_fma_f32 v[26:27], v[80:81], v[40:41], v[26:27]
	v_pk_fma_f32 v[28:29], v[78:79], v[40:41], v[28:29]
	v_pk_fma_f32 v[30:31], v[76:77], v[40:41], v[30:31]
	v_lshlrev_b32_e32 v44, 16, v172
	v_and_b32_e32 v45, 0xffff0000, v172
	v_pk_fma_f32 v[16:17], v[92:93], v[42:43], v[16:17]
	v_pk_fma_f32 v[18:19], v[90:91], v[42:43], v[18:19]
	v_pk_fma_f32 v[20:21], v[88:89], v[42:43], v[20:21]
	v_pk_fma_f32 v[22:23], v[86:87], v[42:43], v[22:23]
	v_pk_fma_f32 v[24:25], v[84:85], v[42:43], v[24:25]
	v_pk_fma_f32 v[26:27], v[82:83], v[42:43], v[26:27]
	v_pk_fma_f32 v[28:29], v[80:81], v[42:43], v[28:29]
	v_pk_fma_f32 v[30:31], v[78:79], v[42:43], v[30:31]
	v_lshlrev_b32_e32 v38, 16, v173
	v_and_b32_e32 v39, 0xffff0000, v173
	v_pk_fma_f32 v[18:19], v[92:93], v[44:45], v[18:19]
	v_pk_fma_f32 v[20:21], v[90:91], v[44:45], v[20:21]
	v_pk_fma_f32 v[22:23], v[88:89], v[44:45], v[22:23]
	v_pk_fma_f32 v[24:25], v[86:87], v[44:45], v[24:25]
	v_pk_fma_f32 v[26:27], v[84:85], v[44:45], v[26:27]
	v_pk_fma_f32 v[28:29], v[82:83], v[44:45], v[28:29]
	v_pk_fma_f32 v[30:31], v[80:81], v[44:45], v[30:31]
	v_lshlrev_b32_e32 v40, 16, v174
	v_and_b32_e32 v41, 0xffff0000, v174
	v_pk_fma_f32 v[20:21], v[92:93], v[38:39], v[20:21]
	v_pk_fma_f32 v[22:23], v[90:91], v[38:39], v[22:23]
	v_pk_fma_f32 v[24:25], v[88:89], v[38:39], v[24:25]
	v_pk_fma_f32 v[26:27], v[86:87], v[38:39], v[26:27]
	v_pk_fma_f32 v[28:29], v[84:85], v[38:39], v[28:29]
	v_pk_fma_f32 v[30:31], v[82:83], v[38:39], v[30:31]
	v_lshlrev_b32_e32 v42, 16, v175
	v_and_b32_e32 v43, 0xffff0000, v175
	v_pk_fma_f32 v[22:23], v[92:93], v[40:41], v[22:23]
; #define LAS __attribute__((address_space(3)))
; __global__ void __launch_bounds__(512, 2) fwd_kernel(Args a) {
;     ...
;             for (int j = 0; j < 31; ++j) {
; #pragma unroll
;                 for (int r = 0; r < 16; ++r) { const unsigned w = *(const LAS unsigned*)(lds + (r + j) * 2048 + tid * 4);
;                     acc[r][0] += wv[j][0] * bflo(w); acc[r][1] += wv[j][1] * bfhi(w); } }
;             __syncthreads();
; #pragma unroll
;             for (int r = 0; r < 16; ++r) { f32x2_t v = {acc[r][0], acc[r][1]}; *(LAS f32x2_t*)(lds + r * 4096 + tid * 8) = v; }
;             __syncthreads();
;             for (int rr = 0; rr < 2; ++rr) { const int r = wave * 2 + rr, t = t0 + r;
;                 if (t < LSEQ) {
;                     f32x4 v[4]; float s = 0.f;
; #pragma unroll
;                     for (int j = 0; j < 4; ++j) { v[j] = *(const LAS f32x4*)(lds + r * 4096 + (lane + 64 * j) * 16); s += (v[j].x + v[j].y) + (v[j].z + v[j].w); }
;                     const float mu = wave_sum(s) * (1.0f / DM); float s2 = 0.f;
	v_pk_fma_f32 v[24:25], v[90:91], v[40:41], v[24:25]
	v_pk_fma_f32 v[26:27], v[88:89], v[40:41], v[26:27]
	v_pk_fma_f32 v[28:29], v[86:87], v[40:41], v[28:29]
	v_pk_fma_f32 v[30:31], v[84:85], v[40:41], v[30:31]
	v_lshlrev_b32_e32 v44, 16, v176
	v_and_b32_e32 v45, 0xffff0000, v176
	v_pk_fma_f32 v[24:25], v[92:93], v[42:43], v[24:25]
	v_pk_fma_f32 v[26:27], v[90:91], v[42:43], v[26:27]
	v_pk_fma_f32 v[28:29], v[88:89], v[42:43], v[28:29]
	v_pk_fma_f32 v[30:31], v[86:87], v[42:43], v[30:31]
	v_lshlrev_b32_e32 v38, 16, v177
	v_and_b32_e32 v39, 0xffff0000, v177
	v_pk_fma_f32 v[26:27], v[92:93], v[44:45], v[26:27]
	v_pk_fma_f32 v[28:29], v[90:91], v[44:45], v[28:29]
	v_pk_fma_f32 v[30:31], v[88:89], v[44:45], v[30:31]
	v_lshlrev_b32_e32 v40, 16, v178
	v_and_b32_e32 v41, 0xffff0000, v178
	v_pk_fma_f32 v[28:29], v[92:93], v[38:39], v[28:29]
	v_pk_fma_f32 v[30:31], v[90:91], v[38:39], v[30:31]
	v_pk_fma_f32 v[30:31], v[92:93], v[40:41], v[30:31]
	v_add_u32_e32 v32, v157, v156
	ds_write2st64_b64 v32, v[0:1], v[2:3] offset1:8
	ds_write2st64_b64 v32, v[4:5], v[6:7] offset0:16 offset1:24
	ds_write2st64_b64 v32, v[8:9], v[10:11] offset0:32 offset1:40
	ds_write2st64_b64 v32, v[12:13], v[14:15] offset0:48 offset1:56
	ds_write2st64_b64 v32, v[16:17], v[18:19] offset0:64 offset1:72
	ds_write2st64_b64 v32, v[20:21], v[22:23] offset0:80 offset1:88
	ds_write2st64_b64 v32, v[24:25], v[26:27] offset0:96 offset1:104
	ds_write2st64_b64 v32, v[28:29], v[30:31] offset0:112 offset1:120
	v_add_u32_e32 v16, s12, v158
	v_cmp_gt_i32_e32 vcc, s15, v16
	v_mbcnt_hi_u32_b32 v18, -1, v182
	s_waitcnt lgkmcnt(0)
	s_barrier
	s_and_saveexec_b64 s[12:13], vcc
	s_cbranch_execz .LBB0_1195
	v_add_u32_e32 v17, v159, v165
	ds_read_b128 v[12:15], v17
	ds_read_b128 v[8:11], v17 offset:1024
	ds_read_b128 v[4:7], v17 offset:2048
	v_and_b32_e32 v19, 64, v18
	v_add_u32_e32 v19, 64, v19
	s_waitcnt lgkmcnt(2)
	v_mov_b32_e32 v0, v13
	v_mov_b32_e32 v1, v14
	v_mov_b32_e32 v2, v12
	v_mov_b32_e32 v3, v15
	v_pk_add_f32 v[0:1], v[0:1], v[2:3]
	s_waitcnt lgkmcnt(1)
	v_mov_b32_e32 v22, v9
	v_add_f32_e32 v0, v0, v1
	v_add_f32_e32 v20, 0, v0
	ds_read_b128 v[0:3], v17 offset:3072
	v_mov_b32_e32 v23, v10
	v_mov_b32_e32 v24, v8
	v_mov_b32_e32 v25, v11
	v_pk_add_f32 v[22:23], v[22:23], v[24:25]
	s_waitcnt lgkmcnt(1)
	v_add_f32_e32 v24, v4, v5
	v_pk_add_f32 v[22:23], v[22:23], v[22:23] op_sel:[0,1] op_sel_hi:[1,0]
	v_add_f32_e32 v26, v6, v7
	s_waitcnt lgkmcnt(0)
	v_mov_b32_e32 v21, v0
	v_mov_b32_e32 v23, v1
	v_mov_b32_e32 v25, v2
	v_mov_b32_e32 v27, v3
	v_pk_add_f32 v[20:21], v[20:21], v[22:23]
	v_pk_add_f32 v[22:23], v[24:25], v[26:27]
	s_nop 0
	v_pk_add_f32 v[20:21], v[20:21], v[22:23]
	s_nop 0
	v_add_f32_e32 v17, v20, v21
	s_nop 1
	v_add_f32_dpp v17, v17, v17 quad_perm:[1,0,3,2] row_mask:0xf bank_mask:0xf
	s_nop 1
	v_add_f32_dpp v17, v17, v17 quad_perm:[2,3,0,1] row_mask:0xf bank_mask:0xf
	s_nop 1
	v_add_f32_dpp v17, v17, v17 row_half_mirror row_mask:0xf bank_mask:0xf
	s_nop 1
	v_add_f32_dpp v17, v17, v17 row_mirror row_mask:0xf bank_mask:0xf
	v_xor_b32_e32 v20, 16, v18
	v_cmp_lt_i32_e32 vcc, v20, v19
	s_nop 1
	v_cndmask_b32_e32 v20, v18, v20, vcc
	v_lshlrev_b32_e32 v36, 2, v20
	ds_bpermute_b32 v20, v36, v17
	s_waitcnt lgkmcnt(0)
	v_add_f32_e32 v17, v17, v20
	v_mov_b32_e32 v20, v17
	s_nop 1
	v_permlane32_swap_b32_e32 v20, v17
	v_add_f32_e32 v17, v17, v20
	v_fmamk_f32 v13, v17, 0xba800000, v13
	v_fmamk_f32 v12, v17, 0xba800000, v12
	v_fmamk_f32 v15, v17, 0xba800000, v15
	v_fmac_f32_e32 v14, 0xba800000, v17
	v_pk_mul_f32 v[20:21], v[14:15], v[14:15]
	v_pk_mul_f32 v[22:23], v[12:13], v[12:13]
	v_fmamk_f32 v9, v17, 0xba800000, v9
	v_pk_mov_b32 v[24:25], v[22:23], v[20:21] op_sel:[1,0]
	v_mov_b32_e32 v23, v21
	v_fmamk_f32 v8, v17, 0xba800000, v8
	v_fmamk_f32 v11, v17, 0xba800000, v11
	v_fmac_f32_e32 v10, 0xba800000, v17
	v_pk_add_f32 v[20:21], v[24:25], v[22:23]
	v_pk_mul_f32 v[22:23], v[10:11], v[10:11]
	v_pk_mul_f32 v[24:25], v[8:9], v[8:9]
	v_fmamk_f32 v1, v17, 0xba800000, v1
	v_pk_mov_b32 v[26:27], v[24:25], v[22:23] op_sel:[1,0]
	v_mov_b32_e32 v25, v23
	v_pk_add_f32 v[22:23], v[26:27], v[24:25]
	v_fmac_f32_e32 v0, 0xba800000, v17
	v_fmamk_f32 v5, v17, 0xba800000, v5
	v_fmamk_f32 v4, v17, 0xba800000, v4
	v_fmamk_f32 v7, v17, 0xba800000, v7
	v_fmac_f32_e32 v6, 0xba800000, v17
	v_fmamk_f32 v3, v17, 0xba800000, v3
	v_fmamk_f32 v2, v17, 0xba800000, v2
	v_mul_f32_e32 v17, v0, v0
	v_mul_f32_e32 v24, v1, v1
	v_pk_add_f32 v[20:21], v[20:21], v[20:21] op_sel:[0,1] op_sel_hi:[1,0]
	v_pk_add_f32 v[22:23], v[22:23], v[22:23] op_sel:[0,1] op_sel_hi:[1,0]
	v_mov_b32_e32 v21, v17
	v_mov_b32_e32 v23, v24
	v_pk_add_f32 v[28:29], v[20:21], v[22:23]
	v_mul_f32_e32 v20, v5, v5
	v_mul_f32_e32 v22, v7, v7
	v_mul_f32_e32 v25, v2, v2
	v_mul_f32_e32 v26, v3, v3
	v_pk_fma_f32 v[20:21], v[4:5], v[4:5], v[20:21] op_sel_hi:[1,1,0]
	v_pk_fma_f32 v[22:23], v[6:7], v[6:7], v[22:23] op_sel_hi:[1,1,0]
	v_mov_b32_e32 v21, v25
	v_mov_b32_e32 v23, v26
	v_pk_add_f32 v[30:31], v[20:21], v[22:23]
	v_pk_add_f32 v[28:29], v[28:29], v[30:31]
	s_nop 0
	v_add_f32_e32 v17, v28, v29
	s_nop 1
	v_add_f32_dpp v17, v17, v17 quad_perm:[1,0,3,2] row_mask:0xf bank_mask:0xf
	s_nop 1
	v_add_f32_dpp v17, v17, v17 quad_perm:[2,3,0,1] row_mask:0xf bank_mask:0xf
	s_nop 1
	v_add_f32_dpp v17, v17, v17 row_half_mirror row_mask:0xf bank_mask:0xf
	s_nop 1
	v_add_f32_dpp v17, v17, v17 row_mirror row_mask:0xf bank_mask:0xf
	ds_bpermute_b32 v28, v36, v17
	s_waitcnt lgkmcnt(0)
; __device__ __forceinline__ unsigned pk2(float lo, float hi) { f32x2_t v = {lo, hi}; bf16x2_t b = __builtin_convertvector(v, bf16x2_t); return __builtin_bit_cast(unsigned, b); }
; __device__ __forceinline__ float sigmoidf_(float x) { return __builtin_amdgcn_rcpf(1.0f + __expf(-x)); }
; __global__ void __launch_bounds__(512, 2) fwd_kernel(Args a) {
;     ...
;                     const float mu = wave_sum(s) * (1.0f / DM); float s2 = 0.f;
; #pragma unroll
;                     for (int j = 0; j < 4; ++j) { v[j] = v[j] - mu; s2 += (v[j].x * v[j].x + v[j].y * v[j].y) + (v[j].z * v[j].z + v[j].w * v[j].w); }
;                     const float rstd = 1.0f / sqrtf(wave_sum(s2) * (1.0f / DM) + 1e-5f);
; #pragma unroll
;                     for (int j = 0; j < 4; ++j) { const f32x4 gv = *((const f32x4*)a.c_lng + lane + 64 * j), bv = *((const f32x4*)a.c_lnb + lane + 64 * j);
;                         f32x4 y = v[j] * rstd * gv + bv; y.x *= sigmoidf_(y.x); y.y *= sigmoidf_(y.y); y.z *= sigmoidf_(y.z); y.w *= sigmoidf_(y.w);
;                         u32x2 o; o.x = pk2(y.x, y.y); o.y = pk2(y.z, y.w); *((u32x2*)(Z + (rb + t) * DM) + lane + 64 * j) = o; }
	v_add_f32_e32 v17, v17, v28
	v_mov_b32_e32 v19, v17
	s_nop 1
	v_permlane32_swap_b32_e32 v19, v17
	v_add_f32_e32 v17, v17, v19
	v_fmamk_f32 v17, v17, 0x3a800000, v204
	v_mul_f32_e32 v19, 0x4f800000, v17
	v_cmp_gt_f32_e32 vcc, s16, v17
	s_nop 1
	v_cndmask_b32_e32 v17, v17, v19, vcc
	v_sqrt_f32_e32 v19, v17
	s_nop 0
	v_add_u32_e32 v28, -1, v19
	v_fma_f32 v29, -v28, v19, v17
	v_cmp_ge_f32_e64 s[0:1], 0, v29
	v_add_u32_e32 v29, 1, v19
	s_nop 0
	v_cndmask_b32_e64 v28, v19, v28, s[0:1]
	v_fma_f32 v19, -v29, v19, v17
	v_cmp_lt_f32_e64 s[0:1], 0, v19
	s_nop 1
	v_cndmask_b32_e64 v19, v28, v29, s[0:1]
	v_mul_f32_e32 v28, 0x37800000, v19
	v_cndmask_b32_e32 v19, v19, v28, vcc
	v_cmp_class_f32_e32 vcc, v17, v205
	s_nop 1
	v_cndmask_b32_e32 v17, v19, v17, vcc
	v_div_scale_f32 v19, s[0:1], v17, v17, 1.0
	v_rcp_f32_e32 v28, v19
	s_nop 0
	v_fma_f32 v29, -v19, v28, 1.0
	v_fmac_f32_e32 v28, v29, v28
	v_div_scale_f32 v29, vcc, 1.0, v17, 1.0
	v_mul_f32_e32 v30, v29, v28
	v_fma_f32 v31, -v19, v30, v29
	v_fmac_f32_e32 v30, v31, v28
	v_fma_f32 v19, -v19, v30, v29
	v_div_fmas_f32 v19, v19, v28, v30
	v_div_fixup_f32 v28, v19, v17, 1.0
	v_pk_mul_f32 v[12:13], v[28:29], v[12:13] op_sel_hi:[0,1]
	v_ashrrev_i32_e32 v17, 31, v16
	v_pk_fma_f32 v[12:13], v[12:13], v[212:213], v[228:229]
	v_lshl_add_u64 v[30:31], s[10:11], 0, v[16:17]
	v_mul_f32_e32 v17, 0xbfb8aa3b, v12
	v_exp_f32_e32 v17, v17
	v_mul_f32_e32 v19, 0xbfb8aa3b, v13
	v_exp_f32_e32 v19, v19
	v_pk_mul_f32 v[14:15], v[28:29], v[14:15] op_sel_hi:[0,1]
	v_pk_fma_f32 v[14:15], v[14:15], v[214:215], v[230:231]
	v_add_f32_e32 v17, 1.0, v17
	v_rcp_f32_e32 v20, v17
	v_add_f32_e32 v17, 1.0, v19
	v_mul_f32_e32 v19, 0xbfb8aa3b, v14
	v_exp_f32_e32 v19, v19
	v_mul_f32_e32 v21, 0xbfb8aa3b, v15
	v_exp_f32_e32 v23, v21
	v_rcp_f32_e32 v21, v17
	v_add_f32_e32 v17, 1.0, v19
	v_rcp_f32_e32 v22, v17
	v_add_f32_e32 v17, 1.0, v23
	v_rcp_f32_e32 v23, v17
	v_lshlrev_b64 v[24:25], 11, v[30:31]
	v_pk_mul_f32 v[12:13], v[12:13], v[20:21]
	v_lshl_add_u64 v[24:25], v[120:121], 0, v[24:25]
	v_pk_mul_f32 v[14:15], v[14:15], v[22:23]
	v_cvt_pk_bf16_f32 v12, v12, v13
	v_cvt_pk_bf16_f32 v13, v14, v15
	global_store_dwordx2 v[24:25], v[12:13], off
	s_nop 0
	v_pk_mul_f32 v[8:9], v[28:29], v[8:9] op_sel_hi:[0,1]
	v_pk_mul_f32 v[10:11], v[28:29], v[10:11] op_sel_hi:[0,1]
	v_pk_mul_f32 v[4:5], v[28:29], v[4:5] op_sel_hi:[0,1]
	v_pk_mul_f32 v[6:7], v[28:29], v[6:7] op_sel_hi:[0,1]
	v_pk_mul_f32 v[0:1], v[28:29], v[0:1] op_sel_hi:[0,1]
	v_pk_mul_f32 v[2:3], v[28:29], v[2:3] op_sel_hi:[0,1]
	v_pk_fma_f32 v[10:11], v[10:11], v[218:219], v[234:235]
	v_pk_fma_f32 v[8:9], v[8:9], v[216:217], v[232:233]
	v_mul_f32_e32 v14, 0xbfb8aa3b, v10
	v_mul_f32_e32 v12, 0xbfb8aa3b, v8
	v_mul_f32_e32 v13, 0xbfb8aa3b, v9
	v_mul_f32_e32 v15, 0xbfb8aa3b, v11
	v_exp_f32_e32 v12, v12
	v_exp_f32_e32 v13, v13
	v_exp_f32_e32 v14, v14
	v_exp_f32_e32 v15, v15
	v_add_f32_e32 v12, 1.0, v12
	v_add_f32_e32 v13, 1.0, v13
	v_add_f32_e32 v14, 1.0, v14
	v_add_f32_e32 v15, 1.0, v15
	v_rcp_f32_e32 v12, v12
	v_rcp_f32_e32 v13, v13
	v_rcp_f32_e32 v14, v14
	v_rcp_f32_e32 v15, v15
	v_pk_mul_f32 v[8:9], v[8:9], v[12:13]
	s_nop 0
	v_cvt_pk_bf16_f32 v8, v8, v9
	v_pk_mul_f32 v[10:11], v[10:11], v[14:15]
	s_nop 0
	v_cvt_pk_bf16_f32 v9, v10, v11
	global_store_dwordx2 v[24:25], v[8:9], off offset:512
	s_nop 0
	v_pk_fma_f32 v[6:7], v[6:7], v[222:223], v[238:239]
	v_pk_fma_f32 v[4:5], v[4:5], v[220:221], v[236:237]
	v_mul_f32_e32 v10, 0xbfb8aa3b, v6
	v_mul_f32_e32 v8, 0xbfb8aa3b, v4
	v_mul_f32_e32 v9, 0xbfb8aa3b, v5
	v_mul_f32_e32 v11, 0xbfb8aa3b, v7
	v_exp_f32_e32 v8, v8
	v_exp_f32_e32 v9, v9
	v_exp_f32_e32 v10, v10
	v_exp_f32_e32 v11, v11
	v_add_f32_e32 v8, 1.0, v8
	v_add_f32_e32 v9, 1.0, v9
	v_add_f32_e32 v10, 1.0, v10
	v_add_f32_e32 v11, 1.0, v11
	v_rcp_f32_e32 v8, v8
	v_rcp_f32_e32 v9, v9
	v_rcp_f32_e32 v10, v10
	v_rcp_f32_e32 v11, v11
	v_pk_mul_f32 v[4:5], v[4:5], v[8:9]
	s_nop 0
	v_cvt_pk_bf16_f32 v4, v4, v5
	v_pk_mul_f32 v[6:7], v[6:7], v[10:11]
	s_nop 0
	v_cvt_pk_bf16_f32 v5, v6, v7
	global_store_dwordx2 v[24:25], v[4:5], off offset:1024
	s_nop 0
	v_pk_fma_f32 v[2:3], v[2:3], v[226:227], v[242:243]
	v_pk_fma_f32 v[0:1], v[0:1], v[224:225], v[240:241]
	v_mul_f32_e32 v6, 0xbfb8aa3b, v2
	v_mul_f32_e32 v4, 0xbfb8aa3b, v0
	v_mul_f32_e32 v5, 0xbfb8aa3b, v1
	v_mul_f32_e32 v7, 0xbfb8aa3b, v3
	v_exp_f32_e32 v4, v4
	v_exp_f32_e32 v5, v5
	v_exp_f32_e32 v6, v6
	v_exp_f32_e32 v7, v7
	v_add_f32_e32 v4, 1.0, v4
	v_add_f32_e32 v5, 1.0, v5
	v_add_f32_e32 v6, 1.0, v6
	v_add_f32_e32 v7, 1.0, v7
	v_rcp_f32_e32 v4, v4
	v_rcp_f32_e32 v5, v5
	v_rcp_f32_e32 v6, v6
	v_rcp_f32_e32 v7, v7
	v_pk_mul_f32 v[0:1], v[0:1], v[4:5]
	s_nop 0
	v_cvt_pk_bf16_f32 v0, v0, v1
	v_pk_mul_f32 v[2:3], v[2:3], v[6:7]
	s_nop 0
	v_cvt_pk_bf16_f32 v1, v2, v3
	global_store_dwordx2 v[24:25], v[0:1], off offset:1536
